# dropped 128 redundant canonicalizing v_max_f32 x,z,z in the stick-breaking score code (v_max 0,z gives the same value)
# baseline (speedup 1.0000x reference)
; #define LAS __attribute__((address_space(3)))
; #define MFMA32(a, b, c) __builtin_amdgcn_mfma_f32_32x32x16_bf16((a), (b), (c), 0, 0, 0)
; __device__ __forceinline__ float fexp2(float x) { return __builtin_amdgcn_exp2f(x); }
; __device__ __forceinline__ float flog2(float x) { return __builtin_amdgcn_logf(x); }
; __device__ __forceinline__ void stick_block(f32x16& s, float& Rr, int t, int kbase, int h, bool diag) {
;     float u[16], gs[4], pg[4];
; #pragma unroll
;     for (int i = 0; i < 16; ++i) {
;         const float z = s[i];
;         const float sp = fmaxf(z, 0.f) + flog2(1.0f + fexp2(-fabsf(z)));
;         const int j = kbase + (i & 3) + 8 * (i >> 2) + 4 * h;
;         const bool valid = !diag || (j < t);
;         u[i] = valid ? -sp : 0.f;
;         s[i] = valid ? (z - sp) : -__builtin_inff();
;     }
; __device__ __forceinline__ void qk_tile(LAS unsigned char* ks, const bf16x8 (&qf)[4], int r, int h, f32x16& s0, f32x16& s1) {
;     bf16x8 kf[8];
; #pragma unroll
;     for (int kk = 0; kk < 4; ++kk) {
;         kf[2 * kk]     = *(const LAS bf16x8*)(ks + (r * KPITCH + 16 * kk + 8 * h) * 2);
;         kf[2 * kk + 1] = *(const LAS bf16x8*)(ks + ((32 + r) * KPITCH + 16 * kk + 8 * h) * 2);
;     }
; #pragma unroll
;     for (int i = 0; i < 16; ++i) { s0[i] = 0.f; s1[i] = 0.f; }
; #pragma unroll
;     for (int kk = 0; kk < 4; ++kk) { s0 = MFMA32(kf[2 * kk], qf[kk], s0); s1 = MFMA32(kf[2 * kk + 1], qf[kk], s1); }
.LBB0_617:
	s_sub_i32 s44, s36, 63
	s_add_i32 s3, s36, 0xffffff81
	s_cmp_lg_u32 s30, 0
	s_cselect_b64 s[8:9], -1, 0
	v_cmp_le_i32_e64 s[14:15], s3, v139
	v_cmp_le_i32_e32 vcc, s44, v139
	s_and_b64 s[8:9], s[8:9], s[14:15]
	s_xor_b64 s[58:59], s[18:19], -1
	s_and_b64 s[18:19], vcc, s[58:59]
	s_and_b64 s[14:15], s[8:9], s[58:59]
	s_mul_i32 s3, s37, 0x2400
	s_and_b64 s[8:9], s[18:19], s[14:15]
	s_add_i32 s45, s3, 0
	s_xor_b64 s[8:9], s[8:9], -1
	s_and_saveexec_b64 s[60:61], s[8:9]
	s_xor_b64 s[60:61], exec, s[60:61]
	s_cbranch_execz .LBB0_627
	s_xor_b64 s[8:9], s[18:19], -1
	s_and_saveexec_b64 s[18:19], s[8:9]
	s_xor_b64 s[18:19], exec, s[18:19]
	s_cbranch_execz .LBB0_622
	s_and_saveexec_b64 s[62:63], s[14:15]
	s_cbranch_execz .LBB0_621
	v_add3_u32 v38, s45, v204, v205
	ds_read_b128 v[50:53], v38 offset:13824
	ds_read_b128 v[34:37], v38 offset:9216
	ds_read_b128 v[66:69], v38 offset:9248
	ds_read_b128 v[70:73], v38 offset:13856
	ds_read_b128 v[74:77], v38 offset:9280
	ds_read_b128 v[78:81], v38 offset:13888
	ds_read_b128 v[82:85], v38 offset:9312
	ds_read_b128 v[86:89], v38 offset:13920
	s_waitcnt lgkmcnt(7)
	v_mfma_f32_32x32x16_bf16 v[50:65], v[50:53], v[98:101], 0
	v_cmp_gt_i32_e32 vcc, s44, v137
	s_waitcnt lgkmcnt(4)
	v_mfma_f32_32x32x16_bf16 v[50:65], v[70:73], v[102:105], v[50:65]
	s_waitcnt lgkmcnt(2)
	v_mfma_f32_32x32x16_bf16 v[50:65], v[78:81], v[106:109], v[50:65]
	v_mfma_f32_32x32x16_bf16 v[34:49], v[34:37], v[98:101], 0
	s_waitcnt lgkmcnt(0)
	v_mfma_f32_32x32x16_bf16 v[50:65], v[86:89], v[110:113], v[50:65]
	v_mfma_f32_32x32x16_bf16 v[34:49], v[66:69], v[102:105], v[34:49]
	s_nop 10
	v_exp_f32_e64 v69, -|v50|
	v_add_u32_e32 v67, s36, v198
	v_add_u32_e32 v66, 0xffffffa1, v67
	v_add_f32_e32 v69, 1.0, v69
	v_log_f32_e32 v69, v69
	v_max_f32_e32 v68, 0, v50
	v_cmp_ge_i32_e64 s[14:15], v66, v138
	s_and_b64 s[14:15], vcc, s[14:15]
	v_add_f32_e32 v68, v68, v69
	v_mfma_f32_32x32x16_bf16 v[34:49], v[74:77], v[106:109], v[34:49]
	v_cndmask_b32_e64 v74, -v68, 0, s[14:15]
	v_sub_f32_e32 v50, v50, v68
	v_exp_f32_e64 v68, -|v51|
	v_cndmask_b32_e64 v66, v50, v238, s[14:15]
	v_max_f32_e32 v50, 0, v51
	v_add_f32_e32 v68, 1.0, v68
	v_log_f32_e32 v68, v68
	v_mfma_f32_32x32x16_bf16 v[34:49], v[82:85], v[110:113], v[34:49]
	v_add_u32_e32 v81, 0xffffff81, v67
	v_add_f32_e32 v50, v50, v68
	v_add_u32_e32 v68, 0xffffffa2, v67
	v_cmp_ge_i32_e64 s[14:15], v68, v138
	s_and_b64 s[14:15], vcc, s[14:15]
	s_nop 0
	v_cndmask_b32_e64 v68, -v50, 0, s[14:15]
	v_sub_f32_e32 v50, v51, v50
	v_exp_f32_e64 v51, -|v52|
	v_cndmask_b32_e64 v69, v50, v238, s[14:15]
	v_max_f32_e32 v50, 0, v52
	v_add_f32_e32 v51, 1.0, v51
	v_log_f32_e32 v51, v51
	s_nop 0
	v_add_f32_e32 v50, v50, v51
	v_add_u32_e32 v51, 0xffffffa3, v67
	v_cmp_ge_i32_e64 s[14:15], v51, v138
	v_exp_f32_e64 v51, -|v53|
	s_and_b64 s[14:15], vcc, s[14:15]
	v_cndmask_b32_e64 v70, -v50, 0, s[14:15]
	v_sub_f32_e32 v50, v52, v50
	v_add_f32_e32 v51, 1.0, v51
	v_log_f32_e32 v51, v51
	v_cndmask_b32_e64 v71, v50, v238, s[14:15]
	v_max_f32_e32 v50, 0, v53
	v_add_f32_e32 v50, v50, v51
	v_add_u32_e32 v51, 0xffffffa4, v67
	v_cmp_ge_i32_e64 s[14:15], v51, v138
	v_exp_f32_e64 v51, -|v54|
	v_exp_f32_e64 v52, -|v55|
	s_and_b64 s[14:15], vcc, s[14:15]
	v_cndmask_b32_e64 v72, -v50, 0, s[14:15]
	v_add_f32_e32 v51, 1.0, v51
	v_log_f32_e32 v51, v51
	v_sub_f32_e32 v50, v53, v50
	v_cndmask_b32_e64 v73, v50, v238, s[14:15]
	v_add_f32_e32 v52, 1.0, v52
	v_max_f32_e32 v50, 0, v54
	v_log_f32_e32 v52, v52
	v_add_f32_e32 v50, v50, v51
	v_add_u32_e32 v51, 0xffffffa9, v67
	v_exp_f32_e64 v53, -|v56|
	v_cmp_ge_i32_e64 s[14:15], v51, v138
	s_and_b64 s[14:15], vcc, s[14:15]
	v_max_f32_e32 v51, 0, v55
	v_cndmask_b32_e64 v75, -v50, 0, s[14:15]
	v_sub_f32_e32 v50, v54, v50
	v_add_f32_e32 v51, v51, v52
	v_add_u32_e32 v52, 0xffffffaa, v67
	v_cndmask_b32_e64 v50, v50, v238, s[14:15]
	v_cmp_ge_i32_e64 s[14:15], v52, v138
	v_add_f32_e32 v53, 1.0, v53
	s_and_b64 s[14:15], vcc, s[14:15]
	v_log_f32_e32 v53, v53
	v_cndmask_b32_e64 v52, -v51, 0, s[14:15]
	v_sub_f32_e32 v51, v55, v51
	v_cndmask_b32_e64 v79, v51, v238, s[14:15]
	v_max_f32_e32 v51, 0, v56
	v_add_f32_e32 v51, v51, v53
	v_add_u32_e32 v53, 0xffffffab, v67
	v_cmp_ge_i32_e64 s[14:15], v53, v138
	v_exp_f32_e64 v53, -|v57|
	s_and_b64 s[14:15], vcc, s[14:15]
	v_cndmask_b32_e64 v80, -v51, 0, s[14:15]
	v_sub_f32_e32 v51, v56, v51
	v_add_f32_e32 v53, 1.0, v53
	v_log_f32_e32 v53, v53
	v_cndmask_b32_e64 v78, v51, v238, s[14:15]
	v_max_f32_e32 v51, 0, v57
	v_add_f32_e32 v51, v51, v53
	v_add_u32_e32 v53, 0xffffffac, v67
	v_cmp_ge_i32_e64 s[14:15], v53, v138
	v_exp_f32_e64 v53, -|v58|
	s_and_b64 s[14:15], vcc, s[14:15]
	v_cndmask_b32_e64 v83, -v51, 0, s[14:15]
	v_sub_f32_e32 v51, v57, v51
	v_add_f32_e32 v53, 1.0, v53
	v_log_f32_e32 v53, v53
	v_cndmask_b32_e64 v84, v51, v238, s[14:15]
	v_max_f32_e32 v51, 0, v58
	v_add_f32_e32 v51, v51, v53
	v_add_u32_e32 v53, 0xffffffb1, v67
	v_cmp_ge_i32_e64 s[14:15], v53, v138
	v_exp_f32_e64 v53, -|v59|
	s_and_b64 s[14:15], vcc, s[14:15]
	v_cndmask_b32_e64 v54, -v51, 0, s[14:15]
	v_sub_f32_e32 v51, v58, v51
	v_add_f32_e32 v53, 1.0, v53
	v_log_f32_e32 v53, v53
	v_cndmask_b32_e64 v58, v51, v238, s[14:15]
	v_max_f32_e32 v51, 0, v59
	v_add_f32_e32 v51, v51, v53
	v_add_u32_e32 v53, 0xffffffb2, v67
	v_cmp_ge_i32_e64 s[14:15], v53, v138
	v_exp_f32_e64 v53, -|v60|
	s_and_b64 s[14:15], vcc, s[14:15]
	v_cndmask_b32_e64 v56, -v51, 0, s[14:15]
	v_sub_f32_e32 v51, v59, v51
	v_add_f32_e32 v53, 1.0, v53
	v_log_f32_e32 v53, v53
	v_cndmask_b32_e64 v59, v51, v238, s[14:15]
	v_max_f32_e32 v51, 0, v60
	v_add_f32_e32 v51, v51, v53
	v_add_u32_e32 v53, 0xffffffb3, v67
	v_cmp_ge_i32_e64 s[14:15], v53, v138
; __device__ __forceinline__ float fexp2(float x) { return __builtin_amdgcn_exp2f(x); }
; __device__ __forceinline__ float flog2(float x) { return __builtin_amdgcn_logf(x); }
; __device__ __forceinline__ void stick_block(f32x16& s, float& Rr, int t, int kbase, int h, bool diag) {
;     float u[16], gs[4], pg[4];
; #pragma unroll
;     for (int i = 0; i < 16; ++i) {
;         const float z = s[i];
;         const float sp = fmaxf(z, 0.f) + flog2(1.0f + fexp2(-fabsf(z)));
;         const int j = kbase + (i & 3) + 8 * (i >> 2) + 4 * h;
;         const bool valid = !diag || (j < t);
;         u[i] = valid ? -sp : 0.f;
;         s[i] = valid ? (z - sp) : -__builtin_inff();
;     }
; #pragma unroll
;     for (int c = 0; c < 4; ++c) { gs[c] = (u[4 * c] + u[4 * c + 1]) + (u[4 * c + 2] + u[4 * c + 3]); pg[c] = __shfl_xor(gs[c], 32); }
;     float run = Rr;
; #pragma unroll
;     for (int c = 3; c >= 0; --c) {
;         float tl = run + ((h == 0) ? pg[c] : 0.f);
; #pragma unroll
;     ...
;         run += gs[c] + pg[c];
;     }
;     Rr = run;
	v_exp_f32_e64 v53, -|v61|
	s_and_b64 s[14:15], vcc, s[14:15]
	v_cndmask_b32_e64 v76, -v51, 0, s[14:15]
	v_sub_f32_e32 v51, v60, v51
	v_add_f32_e32 v53, 1.0, v53
	v_log_f32_e32 v53, v53
	v_cndmask_b32_e64 v77, v51, v238, s[14:15]
	v_max_f32_e32 v51, 0, v61
	v_add_f32_e32 v51, v51, v53
	v_add_u32_e32 v53, 0xffffffb4, v67
	v_cmp_ge_i32_e64 s[14:15], v53, v138
	v_exp_f32_e64 v53, -|v62|
	s_and_b64 s[14:15], vcc, s[14:15]
	v_cndmask_b32_e64 v85, -v51, 0, s[14:15]
	v_sub_f32_e32 v51, v61, v51
	v_add_f32_e32 v53, 1.0, v53
	v_log_f32_e32 v53, v53
	v_cndmask_b32_e64 v86, v51, v238, s[14:15]
	v_max_f32_e32 v51, 0, v62
	v_add_f32_e32 v51, v51, v53
	v_add_u32_e32 v53, 0xffffffb9, v67
	v_cmp_ge_i32_e64 s[14:15], v53, v138
	v_exp_f32_e64 v53, -|v63|
	s_and_b64 s[14:15], vcc, s[14:15]
	v_cndmask_b32_e64 v55, -v51, 0, s[14:15]
	v_sub_f32_e32 v51, v62, v51
	v_add_f32_e32 v53, 1.0, v53
	v_log_f32_e32 v53, v53
	v_cndmask_b32_e64 v87, v51, v238, s[14:15]
	v_max_f32_e32 v51, 0, v63
	v_add_f32_e32 v51, v51, v53
	v_add_u32_e32 v53, 0xffffffba, v67
	v_cmp_ge_i32_e64 s[14:15], v53, v138
	v_exp_f32_e64 v53, -|v64|
	s_and_b64 s[14:15], vcc, s[14:15]
	v_cndmask_b32_e64 v88, -v51, 0, s[14:15]
	v_sub_f32_e32 v51, v63, v51
	v_add_f32_e32 v53, 1.0, v53
	v_log_f32_e32 v53, v53
	v_cndmask_b32_e64 v89, v51, v238, s[14:15]
	v_max_f32_e32 v51, 0, v64
	v_add_f32_e32 v51, v51, v53
	v_add_u32_e32 v53, 0xffffffbb, v67
	v_cmp_ge_i32_e64 s[14:15], v53, v138
	v_exp_f32_e64 v53, -|v65|
	s_and_b64 s[14:15], vcc, s[14:15]
	v_cndmask_b32_e64 v90, -v51, 0, s[14:15]
	v_sub_f32_e32 v51, v64, v51
	v_add_f32_e32 v53, 1.0, v53
	v_log_f32_e32 v53, v53
	v_cndmask_b32_e64 v63, v51, v238, s[14:15]
	v_max_f32_e32 v51, 0, v65
	v_add_f32_e32 v51, v51, v53
	v_add_u32_e32 v53, 0xffffffbc, v67
	v_cmp_ge_i32_e64 s[14:15], v53, v138
	s_and_b64 s[14:15], vcc, s[14:15]
	v_and_b32_e32 v53, 64, v236
	v_cndmask_b32_e64 v64, -v51, 0, s[14:15]
	v_sub_f32_e32 v51, v65, v51
	v_cndmask_b32_e64 v62, v51, v238, s[14:15]
	v_xor_b32_e32 v51, 32, v236
	v_add_u32_e32 v53, 64, v53
	v_cmp_lt_i32_e64 s[14:15], v51, v53
	v_add_f32_e32 v57, v75, v52
	v_add_f32_e32 v60, v80, v83
	v_cndmask_b32_e64 v51, v236, v51, s[14:15]
	v_add_f32_e32 v91, v57, v60
	v_add_f32_e32 v55, v55, v88
	v_add_f32_e32 v57, v90, v64
	v_lshlrev_b32_e32 v82, 2, v51
	v_pk_add_f32 v[54:55], v[54:55], v[56:57]
	ds_bpermute_b32 v61, v82, v55
	v_add_f32_e32 v60, v76, v85
	ds_bpermute_b32 v92, v82, v91
	v_add_f32_e32 v51, v74, v68
	v_cmp_ge_i32_e64 s[14:15], v81, v138
	s_waitcnt lgkmcnt(1)
	v_pk_add_f32 v[54:55], v[54:55], v[60:61]
	v_cndmask_b32_e64 v57, 0, v61, s[12:13]
	ds_bpermute_b32 v132, v82, v54
	v_add_f32_e32 v57, v133, v57
	v_add_f32_e32 v60, v62, v57
	v_add_f32_e32 v57, v64, v57
	v_exp_f32_e32 v62, v60
	v_add_f32_e32 v60, v63, v57
	v_add_f32_e32 v57, v90, v57
	v_exp_f32_e32 v63, v60
	v_add_f32_e32 v60, v89, v57
	v_add_f32_e32 v57, v88, v57
	v_add_f32_e32 v57, v87, v57
	v_exp_f32_e32 v65, v57
	s_waitcnt lgkmcnt(0)
	v_cndmask_b32_e64 v57, 0, v132, s[12:13]
	v_pk_add_f32 v[54:55], v[54:55], v[132:133]
	v_exp_f32_e32 v64, v60
	v_add_f32_e32 v57, v57, v55
	v_add_f32_e32 v60, v86, v57
	v_add_f32_e32 v57, v85, v57
	v_exp_f32_e32 v74, v60
	v_add_f32_e32 v60, v77, v57
	v_add_f32_e32 v57, v76, v57
	v_add_f32_e32 v59, v59, v57
	v_add_f32_e32 v56, v56, v57
	v_exp_f32_e32 v76, v59
	v_add_f32_e32 v56, v58, v56
	v_pk_add_f32 v[58:59], v[54:55], v[54:55] op_sel:[0,1] op_sel_hi:[1,0]
	v_cndmask_b32_e64 v54, 0, v92, s[12:13]
	v_add_f32_e32 v54, v54, v58
	v_add_f32_e32 v55, v84, v54
	v_add_f32_e32 v54, v83, v54
	v_exp_f32_e32 v59, v55
	v_add_f32_e32 v55, v78, v54
	v_add_f32_e32 v54, v80, v54
	v_add_f32_e32 v52, v52, v54
	v_add_f32_e32 v50, v50, v52
	v_exp_f32_e64 v52, -|v34|
	v_exp_f32_e32 v80, v50
	v_max_f32_e32 v50, 0, v34
	v_add_f32_e32 v52, 1.0, v52
	v_log_f32_e32 v52, v52
	s_and_b64 s[14:15], vcc, s[14:15]
	v_exp_f32_e32 v77, v56
	v_exp_f32_e32 v75, v60
	v_add_f32_e32 v50, v50, v52
	v_cndmask_b32_e64 v56, -v50, 0, s[14:15]
	v_sub_f32_e32 v34, v34, v50
	v_exp_f32_e64 v50, -|v35|
	v_cndmask_b32_e64 v81, v34, v238, s[14:15]
	v_max_f32_e32 v34, 0, v35
	v_add_f32_e32 v50, 1.0, v50
	v_log_f32_e32 v50, v50
	v_exp_f32_e32 v78, v55
	v_add_f32_e32 v55, v79, v54
	v_exp_f32_e32 v79, v55
	v_add_f32_e32 v50, v34, v50
	v_add_u32_e32 v34, 0xffffff82, v67
	v_cmp_ge_i32_e64 s[14:15], v34, v138
	s_and_b64 s[14:15], vcc, s[14:15]
	v_sub_f32_e32 v35, v35, v50
	v_cndmask_b32_e64 v34, -v50, 0, s[14:15]
	v_exp_f32_e64 v50, -|v36|
	v_cndmask_b32_e64 v83, v35, v238, s[14:15]
	v_max_f32_e32 v35, 0, v36
	v_add_f32_e32 v50, 1.0, v50
	v_log_f32_e32 v50, v50
	v_add_f32_e32 v55, v91, v92
	v_add_f32_e32 v53, v70, v72
	v_add_f32_e32 v53, v51, v53
	v_add_f32_e32 v35, v35, v50
	v_add_u32_e32 v50, 0xffffff83, v67
	v_cmp_ge_i32_e64 s[14:15], v50, v138
	s_and_b64 s[14:15], vcc, s[14:15]
	v_exp_f32_e64 v50, -|v39|
	v_cndmask_b32_e64 v60, -v35, 0, s[14:15]
	v_sub_f32_e32 v35, v36, v35
	v_exp_f32_e64 v36, -|v37|
	v_cndmask_b32_e64 v84, v35, v238, s[14:15]
	v_max_f32_e32 v35, 0, v37
	v_add_f32_e32 v36, 1.0, v36
	v_log_f32_e32 v36, v36
	v_add_f32_e32 v50, 1.0, v50
	v_log_f32_e32 v50, v50
	ds_bpermute_b32 v51, v82, v53
	v_add_f32_e32 v35, v35, v36
	v_add_u32_e32 v36, 0xffffff84, v67
	v_cmp_ge_i32_e64 s[14:15], v36, v138
	s_and_b64 s[14:15], vcc, s[14:15]
	s_waitcnt lgkmcnt(0)
; __device__ __forceinline__ float fexp2(float x) { return __builtin_amdgcn_exp2f(x); }
; __device__ __forceinline__ float flog2(float x) { return __builtin_amdgcn_logf(x); }
; __device__ __forceinline__ void stick_block(f32x16& s, float& Rr, int t, int kbase, int h, bool diag) {
;     float u[16], gs[4], pg[4];
; #pragma unroll
;     for (int i = 0; i < 16; ++i) {
;         const float z = s[i];
;         const float sp = fmaxf(z, 0.f) + flog2(1.0f + fexp2(-fabsf(z)));
;         const int j = kbase + (i & 3) + 8 * (i >> 2) + 4 * h;
;         const bool valid = !diag || (j < t);
;         u[i] = valid ? -sp : 0.f;
;         s[i] = valid ? (z - sp) : -__builtin_inff();
;     }
; #pragma unroll
;     for (int c = 0; c < 4; ++c) { gs[c] = (u[4 * c] + u[4 * c + 1]) + (u[4 * c + 2] + u[4 * c + 3]); pg[c] = __shfl_xor(gs[c], 32); }
	v_cndmask_b32_e64 v61, 0, v51, s[12:13]
	v_cndmask_b32_e64 v36, -v35, 0, s[14:15]
	v_sub_f32_e32 v35, v37, v35
	v_exp_f32_e64 v37, -|v38|
	v_cndmask_b32_e64 v85, v35, v238, s[14:15]
	v_max_f32_e32 v35, 0, v38
	v_add_f32_e32 v37, 1.0, v37
	v_log_f32_e32 v37, v37
	s_nop 0
	v_add_f32_e32 v37, v35, v37
	v_add_u32_e32 v35, 0xffffff89, v67
	v_cmp_ge_i32_e64 s[14:15], v35, v138
	s_and_b64 s[14:15], vcc, s[14:15]
	s_nop 0
	v_cndmask_b32_e64 v35, -v37, 0, s[14:15]
	v_sub_f32_e32 v37, v38, v37
	v_cndmask_b32_e64 v38, v37, v238, s[14:15]
	v_max_f32_e32 v37, 0, v39
	v_add_f32_e32 v37, v37, v50
	v_add_u32_e32 v50, 0xffffff8a, v67
	v_cmp_ge_i32_e64 s[14:15], v50, v138
	v_exp_f32_e64 v50, -|v40|
	s_and_b64 s[14:15], vcc, s[14:15]
	v_cndmask_b32_e64 v86, -v37, 0, s[14:15]
	v_sub_f32_e32 v37, v39, v37
	v_add_f32_e32 v50, 1.0, v50
	v_log_f32_e32 v50, v50
	v_cndmask_b32_e64 v39, v37, v238, s[14:15]
	v_max_f32_e32 v37, 0, v40
	v_add_f32_e32 v37, v37, v50
	v_add_u32_e32 v50, 0xffffff8b, v67
	v_cmp_ge_i32_e64 s[14:15], v50, v138
	v_exp_f32_e64 v50, -|v41|
	s_and_b64 s[14:15], vcc, s[14:15]
	v_cndmask_b32_e64 v87, -v37, 0, s[14:15]
	v_sub_f32_e32 v37, v40, v37
	v_add_f32_e32 v50, 1.0, v50
	v_log_f32_e32 v50, v50
	v_cndmask_b32_e64 v40, v37, v238, s[14:15]
	v_max_f32_e32 v37, 0, v41
	v_add_f32_e32 v37, v37, v50
	v_add_u32_e32 v50, 0xffffff8c, v67
	v_cmp_ge_i32_e64 s[14:15], v50, v138
	v_exp_f32_e64 v50, -|v42|
	s_and_b64 s[14:15], vcc, s[14:15]
	v_cndmask_b32_e64 v88, -v37, 0, s[14:15]
	v_sub_f32_e32 v37, v41, v37
	v_add_f32_e32 v50, 1.0, v50
	v_log_f32_e32 v50, v50
	v_cndmask_b32_e64 v41, v37, v238, s[14:15]
	v_max_f32_e32 v37, 0, v42
	v_add_f32_e32 v37, v37, v50
	v_add_u32_e32 v50, 0xffffff91, v67
	v_cmp_ge_i32_e64 s[14:15], v50, v138
	v_exp_f32_e64 v50, -|v43|
	s_and_b64 s[14:15], vcc, s[14:15]
	v_cndmask_b32_e64 v89, -v37, 0, s[14:15]
	v_sub_f32_e32 v37, v42, v37
	v_add_f32_e32 v50, 1.0, v50
	v_log_f32_e32 v50, v50
	v_cndmask_b32_e64 v42, v37, v238, s[14:15]
	v_max_f32_e32 v37, 0, v43
	v_add_f32_e32 v37, v37, v50
	v_add_u32_e32 v50, 0xffffff92, v67
	v_cmp_ge_i32_e64 s[14:15], v50, v138
	v_exp_f32_e64 v50, -|v44|
	s_and_b64 s[14:15], vcc, s[14:15]
	v_cndmask_b32_e64 v90, -v37, 0, s[14:15]
	v_sub_f32_e32 v37, v43, v37
	v_add_f32_e32 v50, 1.0, v50
	v_log_f32_e32 v50, v50
	v_cndmask_b32_e64 v43, v37, v238, s[14:15]
	v_max_f32_e32 v37, 0, v44
	v_add_f32_e32 v37, v37, v50
	v_add_u32_e32 v50, 0xffffff93, v67
	v_cmp_ge_i32_e64 s[14:15], v50, v138
	s_and_b64 s[14:15], vcc, s[14:15]
	v_add_f32_e32 v35, v35, v86
	v_cndmask_b32_e64 v91, -v37, 0, s[14:15]
	v_sub_f32_e32 v37, v44, v37
	v_exp_f32_e64 v44, -|v45|
	v_cndmask_b32_e64 v92, v37, v238, s[14:15]
	v_max_f32_e32 v37, 0, v45
	v_add_f32_e32 v44, 1.0, v44
	v_log_f32_e32 v44, v44
	s_nop 0
	v_add_f32_e32 v37, v37, v44
	v_add_u32_e32 v44, 0xffffff94, v67
	v_cmp_ge_i32_e64 s[14:15], v44, v138
	v_exp_f32_e64 v44, -|v46|
	s_and_b64 s[14:15], vcc, s[14:15]
	v_cndmask_b32_e64 v93, -v37, 0, s[14:15]
	v_sub_f32_e32 v37, v45, v37
	v_exp_f32_e64 v45, -|v47|
	v_add_f32_e32 v44, 1.0, v44
	v_log_f32_e32 v44, v44
	v_cndmask_b32_e64 v94, v37, v238, s[14:15]
	v_add_f32_e32 v45, 1.0, v45
	v_max_f32_e32 v37, 0, v46
	v_log_f32_e32 v45, v45
	v_add_f32_e32 v37, v37, v44
	v_add_u32_e32 v44, 0xffffff99, v67
	v_cmp_ge_i32_e64 s[14:15], v44, v138
	s_and_b64 s[14:15], vcc, s[14:15]
	v_max_f32_e32 v44, 0, v47
	v_cndmask_b32_e64 v52, -v37, 0, s[14:15]
	v_sub_f32_e32 v37, v46, v37
	v_add_f32_e32 v44, v44, v45
	v_add_u32_e32 v45, 0xffffff9a, v67
	v_cndmask_b32_e64 v37, v37, v238, s[14:15]
	v_cmp_ge_i32_e64 s[14:15], v45, v138
	v_exp_f32_e64 v45, -|v48|
	s_and_b64 s[14:15], vcc, s[14:15]
	v_cndmask_b32_e64 v50, -v44, 0, s[14:15]
	v_sub_f32_e32 v44, v47, v44
	v_add_f32_e32 v45, 1.0, v45
	v_log_f32_e32 v45, v45
	v_cndmask_b32_e64 v95, v44, v238, s[14:15]
	v_max_f32_e32 v44, 0, v48
	v_add_f32_e32 v44, v44, v45
	v_add_u32_e32 v45, 0xffffff9b, v67
	v_cmp_ge_i32_e64 s[14:15], v45, v138
	v_exp_f32_e64 v45, -|v49|
	s_and_b64 s[14:15], vcc, s[14:15]
	v_cndmask_b32_e64 v54, -v44, 0, s[14:15]
	v_sub_f32_e32 v44, v48, v44
	v_add_f32_e32 v45, 1.0, v45
	v_log_f32_e32 v45, v45
	v_cndmask_b32_e64 v96, v44, v238, s[14:15]
	v_max_f32_e32 v44, 0, v49
	v_add_f32_e32 v45, v44, v45
	v_add_u32_e32 v44, 0xffffff9c, v67
	v_cmp_ge_i32_e64 s[14:15], v44, v138
	s_and_b64 vcc, vcc, s[14:15]
	v_cndmask_b32_e64 v44, -v45, 0, vcc
	v_sub_f32_e32 v45, v49, v45
	v_cndmask_b32_e32 v67, v45, v238, vcc
	v_add_f32_e32 v45, v87, v88
	v_add_f32_e32 v57, v35, v45
	v_add_f32_e32 v45, v89, v90
	v_add_f32_e32 v46, v91, v93
	v_add_f32_e32 v89, v45, v46
	v_mov_b32_e32 v45, v58
	v_pk_add_f32 v[46:47], v[54:55], v[44:45]
	ds_bpermute_b32 v97, v82, v89
	v_add_f32_e32 v45, v61, v47
	v_add_f32_e32 v48, v73, v45
	v_add_f32_e32 v45, v72, v45
	v_exp_f32_e32 v55, v48
	v_add_f32_e32 v48, v71, v45
	v_add_f32_e32 v45, v70, v45
	v_exp_f32_e32 v58, v48
	v_add_f32_e32 v48, v69, v45
	v_exp_f32_e32 v69, v48
	v_add_f32_e32 v45, v68, v45
	v_pk_add_f32 v[48:49], v[52:53], v[50:51]
	v_add_f32_e32 v45, v66, v45
	v_pk_add_f32 v[46:47], v[48:49], v[46:47]
	v_exp_f32_e32 v66, v45
	ds_bpermute_b32 v45, v82, v46
	ds_bpermute_b32 v35, v82, v57
	s_waitcnt lgkmcnt(2)
; #define LAS __attribute__((address_space(3)))
; #define MFMA32(a, b, c) __builtin_amdgcn_mfma_f32_32x32x16_bf16((a), (b), (c), 0, 0, 0)
; __device__ __forceinline__ void stick_block(f32x16& s, float& Rr, int t, int kbase, int h, bool diag) {
;     ...
;     for (int c = 0; c < 4; ++c) { gs[c] = (u[4 * c] + u[4 * c + 1]) + (u[4 * c + 2] + u[4 * c + 3]); pg[c] = __shfl_xor(gs[c], 32); }
;     float run = Rr;
; #pragma unroll
;     for (int c = 3; c >= 0; --c) {
;         float tl = run + ((h == 0) ? pg[c] : 0.f);
; #pragma unroll
;     ...
;         run += gs[c] + pg[c];
;     }
;     Rr = run;
; __device__ __forceinline__ void pv_tile(LAS unsigned char* vt, const f32x16& s0, const f32x16& s1, int h, int lane, f32x16 (&o)[2]) {
; #pragma unroll
;     for (int st = 0; st < 2; ++st) {
;         const bf16x8 pb = pack8(s0, st);
; #pragma unroll
;         for (int db = 0; db < 2; ++db) o[db] = MFMA32(vfrag<64>(vt, 32 * db, 16 * st + 4 * h, lane), pb, o[db]);
;     }
; #pragma unroll
;     for (int st = 0; st < 2; ++st) {
;         const bf16x8 pb = pack8(s1, st);
; #pragma unroll
;         for (int db = 0; db < 2; ++db) o[db] = MFMA32(vfrag<64>(vt, 32 * db, 32 + 16 * st + 4 * h, lane), pb, o[db]);
;     }
	v_add_f32_e32 v61, v89, v97
	s_waitcnt lgkmcnt(1)
	v_cndmask_b32_e64 v48, 0, v45, s[12:13]
	v_add_f32_e32 v48, v48, v47
	v_add_f32_e32 v44, v44, v48
	v_add_f32_e32 v49, v67, v48
	v_add_f32_e32 v48, v96, v44
	v_add_f32_e32 v44, v54, v44
	v_add_f32_e32 v51, v95, v44
	v_add_f32_e32 v44, v50, v44
	v_add_f32_e32 v37, v37, v44
	v_exp_f32_e32 v50, v37
	v_add_f32_e32 v37, v46, v45
	v_add_f32_e32 v37, v37, v47
	v_cndmask_b32_e64 v44, 0, v97, s[12:13]
	v_add_f32_e32 v44, v44, v37
	v_add_f32_e32 v45, v94, v44
	v_add_f32_e32 v44, v93, v44
	v_exp_f32_e32 v46, v45
	v_add_f32_e32 v45, v92, v44
	v_add_f32_e32 v44, v91, v44
	v_add_f32_e32 v43, v43, v44
	v_exp_f32_e32 v52, v43
	v_add_f32_e32 v43, v90, v44
	v_add_f32_e32 v42, v42, v43
	v_exp_f32_e32 v47, v45
	v_exp_f32_e32 v53, v42
	v_pk_add_f32 v[42:43], v[60:61], v[36:37]
	s_waitcnt lgkmcnt(0)
	v_pk_add_f32 v[44:45], v[56:57], v[34:35]
	v_cndmask_b32_e64 v54, 0, v35, s[12:13]
	v_pk_add_f32 v[44:45], v[44:45], v[42:43]
	ds_bpermute_b32 v35, v82, v44
	v_add_f32_e32 v37, v54, v43
	v_add_f32_e32 v41, v41, v37
	v_add_f32_e32 v37, v88, v37
	v_add_f32_e32 v40, v40, v37
	v_add_f32_e32 v37, v87, v37
	v_add_f32_e32 v39, v39, v37
	v_add_f32_e32 v37, v86, v37
	v_add_f32_e32 v37, v38, v37
	s_waitcnt lgkmcnt(0)
	v_cndmask_b32_e64 v38, 0, v35, s[12:13]
	v_add_f32_e32 v38, v38, v45
	v_add_f32_e32 v36, v36, v38
	v_add_f32_e32 v42, v85, v38
	v_add_f32_e32 v38, v84, v36
	v_exp_f32_e32 v42, v42
	v_exp_f32_e32 v38, v38
	v_exp_f32_e32 v41, v41
	v_exp_f32_e32 v40, v40
	v_exp_f32_e32 v39, v39
	v_exp_f32_e32 v37, v37
	v_add_f32_e32 v36, v60, v36
	v_add_f32_e32 v34, v34, v36
	v_add_f32_e32 v35, v44, v35
	v_add_f32_e32 v43, v83, v36
	v_add_f32_e32 v34, v81, v34
	v_add_f32_e32 v133, v35, v45
	v_cvt_pk_bf16_f32 v35, v38, v42
	v_add_u32_e32 v42, s45, v200
	v_exp_f32_e32 v43, v43
	v_exp_f32_e32 v34, v34
	v_cvt_pk_bf16_f32 v36, v37, v39
	v_cvt_pk_bf16_f32 v37, v40, v41
	ds_read_b64_tr_b16 v[38:39], v42 offset:46080
	ds_read_b64_tr_b16 v[40:41], v42 offset:47232
	v_cvt_pk_bf16_f32 v34, v34, v43
	v_exp_f32_e32 v49, v49
	v_exp_f32_e32 v48, v48
	s_waitcnt lgkmcnt(0)
	v_mfma_f32_32x32x16_bf16 v[18:33], v[38:41], v[34:37], v[18:33]
	ds_read_b64_tr_b16 v[38:39], v42 offset:46144
	ds_read_b64_tr_b16 v[40:41], v42 offset:47296
	v_exp_f32_e32 v51, v51
	s_waitcnt lgkmcnt(0)
	v_mfma_f32_32x32x16_bf16 v[2:17], v[38:41], v[34:37], v[2:17]
	ds_read_b64_tr_b16 v[38:39], v42 offset:48384
	ds_read_b64_tr_b16 v[40:41], v42 offset:49536
	v_cvt_pk_bf16_f32 v34, v53, v52
	v_cvt_pk_bf16_f32 v35, v47, v46
	v_cvt_pk_bf16_f32 v36, v50, v51
	v_cvt_pk_bf16_f32 v37, v48, v49
	s_waitcnt lgkmcnt(0)
	s_nop 0
	v_mfma_f32_32x32x16_bf16 v[18:33], v[38:41], v[34:37], v[18:33]
	ds_read_b64_tr_b16 v[38:39], v42 offset:48448
	ds_read_b64_tr_b16 v[40:41], v42 offset:49600
	s_waitcnt lgkmcnt(0)
	v_mfma_f32_32x32x16_bf16 v[2:17], v[38:41], v[34:37], v[2:17]
	ds_read_b64_tr_b16 v[38:39], v42 offset:50688
	ds_read_b64_tr_b16 v[40:41], v42 offset:51840
	v_cvt_pk_bf16_f32 v34, v66, v69
	v_cvt_pk_bf16_f32 v35, v58, v55
	v_cvt_pk_bf16_f32 v36, v80, v79
	v_cvt_pk_bf16_f32 v37, v78, v59
	s_waitcnt lgkmcnt(0)
	s_nop 0
	v_mfma_f32_32x32x16_bf16 v[18:33], v[38:41], v[34:37], v[18:33]
	ds_read_b64_tr_b16 v[38:39], v42 offset:50752
	ds_read_b64_tr_b16 v[40:41], v42 offset:51904
	s_waitcnt lgkmcnt(0)
	v_mfma_f32_32x32x16_bf16 v[2:17], v[38:41], v[34:37], v[2:17]
	ds_read_b64_tr_b16 v[38:39], v42 offset:52992
	ds_read_b64_tr_b16 v[40:41], v42 offset:54144
	v_cvt_pk_bf16_f32 v34, v77, v76
	v_cvt_pk_bf16_f32 v35, v75, v74
	v_cvt_pk_bf16_f32 v36, v65, v64
	v_cvt_pk_bf16_f32 v37, v63, v62
	s_waitcnt lgkmcnt(0)
	s_nop 0
	v_mfma_f32_32x32x16_bf16 v[18:33], v[38:41], v[34:37], v[18:33]
	ds_read_b64_tr_b16 v[38:39], v42 offset:53056
	ds_read_b64_tr_b16 v[40:41], v42 offset:54208
	s_waitcnt lgkmcnt(0)
	v_mfma_f32_32x32x16_bf16 v[2:17], v[38:41], v[34:37], v[2:17]

; #define LAS __attribute__((address_space(3)))
; #define MFMA32(a, b, c) __builtin_amdgcn_mfma_f32_32x32x16_bf16((a), (b), (c), 0, 0, 0)
; __device__ __forceinline__ float fexp2(float x) { return __builtin_amdgcn_exp2f(x); }
; __device__ __forceinline__ float flog2(float x) { return __builtin_amdgcn_logf(x); }
; __device__ __forceinline__ void stick_block(f32x16& s, float& Rr, int t, int kbase, int h, bool diag) {
;     float u[16], gs[4], pg[4];
; #pragma unroll
;     for (int i = 0; i < 16; ++i) {
;         const float z = s[i];
;         const float sp = fmaxf(z, 0.f) + flog2(1.0f + fexp2(-fabsf(z)));
;         const int j = kbase + (i & 3) + 8 * (i >> 2) + 4 * h;
;         const bool valid = !diag || (j < t);
;         u[i] = valid ? -sp : 0.f;
;         s[i] = valid ? (z - sp) : -__builtin_inff();
; __device__ __forceinline__ void qk_tile(LAS unsigned char* ks, const bf16x8 (&qf)[4], int r, int h, f32x16& s0, f32x16& s1) {
;     bf16x8 kf[8];
; #pragma unroll
;     for (int kk = 0; kk < 4; ++kk) {
;         kf[2 * kk]     = *(const LAS bf16x8*)(ks + (r * KPITCH + 16 * kk + 8 * h) * 2);
;         kf[2 * kk + 1] = *(const LAS bf16x8*)(ks + ((32 + r) * KPITCH + 16 * kk + 8 * h) * 2);
;     }
; #pragma unroll
;     for (int i = 0; i < 16; ++i) { s0[i] = 0.f; s1[i] = 0.f; }
; #pragma unroll
;     for (int kk = 0; kk < 4; ++kk) { s0 = MFMA32(kf[2 * kk], qf[kk], s0); s1 = MFMA32(kf[2 * kk + 1], qf[kk], s1); }
; }
.LBB0_622:
	s_andn2_saveexec_b64 s[18:19], s[18:19]
	s_cbranch_execz .LBB0_624
	v_add3_u32 v38, s45, v204, v205
	ds_read_b128 v[50:53], v38 offset:4608
	ds_read_b128 v[34:37], v38
	ds_read_b128 v[66:69], v38 offset:32
	ds_read_b128 v[70:73], v38 offset:4640
	ds_read_b128 v[74:77], v38 offset:64
	ds_read_b128 v[78:81], v38 offset:4672
	ds_read_b128 v[82:85], v38 offset:96
	ds_read_b128 v[86:89], v38 offset:4704
	s_waitcnt lgkmcnt(7)
	v_mfma_f32_32x32x16_bf16 v[50:65], v[50:53], v[98:101], 0
	v_cmp_ge_i32_e32 vcc, s36, v137
	s_waitcnt lgkmcnt(4)
	v_mfma_f32_32x32x16_bf16 v[50:65], v[70:73], v[102:105], v[50:65]
	s_waitcnt lgkmcnt(2)
	v_mfma_f32_32x32x16_bf16 v[50:65], v[78:81], v[106:109], v[50:65]
	v_mfma_f32_32x32x16_bf16 v[34:49], v[34:37], v[98:101], 0
	s_waitcnt lgkmcnt(0)
	v_mfma_f32_32x32x16_bf16 v[50:65], v[86:89], v[110:113], v[50:65]
	v_mfma_f32_32x32x16_bf16 v[34:49], v[66:69], v[102:105], v[34:49]
	s_nop 10
	v_exp_f32_e64 v69, -|v50|
	v_add_u32_e32 v67, s36, v198
	v_subrev_u32_e32 v66, 31, v67
	v_add_f32_e32 v69, 1.0, v69
	v_log_f32_e32 v69, v69
	v_max_f32_e32 v68, 0, v50
	v_cmp_ge_i32_e64 s[14:15], v66, v138
	s_and_b64 s[14:15], vcc, s[14:15]
	v_add_f32_e32 v68, v68, v69
	v_mfma_f32_32x32x16_bf16 v[34:49], v[74:77], v[106:109], v[34:49]
	v_cndmask_b32_e64 v74, -v68, 0, s[14:15]
	v_sub_f32_e32 v50, v50, v68
	v_exp_f32_e64 v68, -|v51|
	v_cndmask_b32_e64 v66, v50, v238, s[14:15]
	v_max_f32_e32 v50, 0, v51
	v_add_f32_e32 v68, 1.0, v68
	v_log_f32_e32 v68, v68
	v_mfma_f32_32x32x16_bf16 v[34:49], v[82:85], v[110:113], v[34:49]
	v_subrev_u32_e32 v81, 63, v67
	v_add_f32_e32 v50, v50, v68
	v_subrev_u32_e32 v68, 30, v67
	v_cmp_ge_i32_e64 s[14:15], v68, v138
	s_and_b64 s[14:15], vcc, s[14:15]
	s_nop 0
	v_cndmask_b32_e64 v68, -v50, 0, s[14:15]
	v_sub_f32_e32 v50, v51, v50
	v_exp_f32_e64 v51, -|v52|
	v_cndmask_b32_e64 v69, v50, v238, s[14:15]
	v_max_f32_e32 v50, 0, v52
	v_add_f32_e32 v51, 1.0, v51
	v_log_f32_e32 v51, v51
	s_nop 0
	v_add_f32_e32 v50, v50, v51
	v_subrev_u32_e32 v51, 29, v67
	v_cmp_ge_i32_e64 s[14:15], v51, v138
	v_exp_f32_e64 v51, -|v53|
	s_and_b64 s[14:15], vcc, s[14:15]
	v_cndmask_b32_e64 v70, -v50, 0, s[14:15]
	v_sub_f32_e32 v50, v52, v50
	v_add_f32_e32 v51, 1.0, v51
	v_log_f32_e32 v51, v51
	v_cndmask_b32_e64 v71, v50, v238, s[14:15]
	v_max_f32_e32 v50, 0, v53
	v_add_f32_e32 v50, v50, v51
	v_subrev_u32_e32 v51, 28, v67
	v_cmp_ge_i32_e64 s[14:15], v51, v138
	v_exp_f32_e64 v51, -|v54|
	v_exp_f32_e64 v52, -|v55|
	s_and_b64 s[14:15], vcc, s[14:15]
	v_cndmask_b32_e64 v72, -v50, 0, s[14:15]
	v_add_f32_e32 v51, 1.0, v51
	v_log_f32_e32 v51, v51
	v_sub_f32_e32 v50, v53, v50
	v_cndmask_b32_e64 v73, v50, v238, s[14:15]
	v_add_f32_e32 v52, 1.0, v52
	v_max_f32_e32 v50, 0, v54
	v_log_f32_e32 v52, v52
	v_add_f32_e32 v50, v50, v51
	v_subrev_u32_e32 v51, 23, v67
	v_exp_f32_e64 v53, -|v56|
	v_cmp_ge_i32_e64 s[14:15], v51, v138
	s_and_b64 s[14:15], vcc, s[14:15]
	v_max_f32_e32 v51, 0, v55
	v_cndmask_b32_e64 v75, -v50, 0, s[14:15]
	v_sub_f32_e32 v50, v54, v50
	v_add_f32_e32 v51, v51, v52
	v_subrev_u32_e32 v52, 22, v67
	v_cndmask_b32_e64 v50, v50, v238, s[14:15]
	v_cmp_ge_i32_e64 s[14:15], v52, v138
	v_add_f32_e32 v53, 1.0, v53
	s_and_b64 s[14:15], vcc, s[14:15]
	v_log_f32_e32 v53, v53
	v_cndmask_b32_e64 v52, -v51, 0, s[14:15]
	v_sub_f32_e32 v51, v55, v51
	v_cndmask_b32_e64 v79, v51, v238, s[14:15]
	v_max_f32_e32 v51, 0, v56
	v_add_f32_e32 v51, v51, v53
	v_subrev_u32_e32 v53, 21, v67
	v_cmp_ge_i32_e64 s[14:15], v53, v138
	v_exp_f32_e64 v53, -|v57|
	s_and_b64 s[14:15], vcc, s[14:15]
	v_cndmask_b32_e64 v80, -v51, 0, s[14:15]
	v_sub_f32_e32 v51, v56, v51
	v_add_f32_e32 v53, 1.0, v53
	v_log_f32_e32 v53, v53
	v_cndmask_b32_e64 v78, v51, v238, s[14:15]
	v_max_f32_e32 v51, 0, v57
	v_add_f32_e32 v51, v51, v53
	v_subrev_u32_e32 v53, 20, v67
	v_cmp_ge_i32_e64 s[14:15], v53, v138
	v_exp_f32_e64 v53, -|v58|
	s_and_b64 s[14:15], vcc, s[14:15]
	v_cndmask_b32_e64 v83, -v51, 0, s[14:15]
	v_sub_f32_e32 v51, v57, v51
	v_add_f32_e32 v53, 1.0, v53
	v_log_f32_e32 v53, v53
	v_cndmask_b32_e64 v84, v51, v238, s[14:15]
	v_max_f32_e32 v51, 0, v58
	v_add_f32_e32 v51, v51, v53
	v_add_u32_e32 v53, -15, v67
	v_cmp_ge_i32_e64 s[14:15], v53, v138
	v_exp_f32_e64 v53, -|v59|
	s_and_b64 s[14:15], vcc, s[14:15]
	v_cndmask_b32_e64 v54, -v51, 0, s[14:15]
	v_sub_f32_e32 v51, v58, v51
	v_add_f32_e32 v53, 1.0, v53
	v_log_f32_e32 v53, v53
	v_cndmask_b32_e64 v58, v51, v238, s[14:15]
	v_max_f32_e32 v51, 0, v59
	v_add_f32_e32 v51, v51, v53
	v_add_u32_e32 v53, -14, v67
	v_cmp_ge_i32_e64 s[14:15], v53, v138
	v_exp_f32_e64 v53, -|v60|
	s_and_b64 s[14:15], vcc, s[14:15]
	v_cndmask_b32_e64 v56, -v51, 0, s[14:15]
	v_sub_f32_e32 v51, v59, v51
	v_add_f32_e32 v53, 1.0, v53
	v_log_f32_e32 v53, v53
	v_cndmask_b32_e64 v59, v51, v238, s[14:15]
	v_max_f32_e32 v51, 0, v60
	v_add_f32_e32 v51, v51, v53
	v_add_u32_e32 v53, -13, v67
	v_cmp_ge_i32_e64 s[14:15], v53, v138
	v_exp_f32_e64 v53, -|v61|
	s_and_b64 s[14:15], vcc, s[14:15]
	v_cndmask_b32_e64 v76, -v51, 0, s[14:15]
	v_sub_f32_e32 v51, v60, v51
	v_add_f32_e32 v53, 1.0, v53
	v_log_f32_e32 v53, v53
	v_cndmask_b32_e64 v77, v51, v238, s[14:15]
	v_max_f32_e32 v51, 0, v61
	v_add_f32_e32 v51, v51, v53
	v_add_u32_e32 v53, -12, v67
	v_cmp_ge_i32_e64 s[14:15], v53, v138
	v_exp_f32_e64 v53, -|v62|
	s_and_b64 s[14:15], vcc, s[14:15]
	v_cndmask_b32_e64 v85, -v51, 0, s[14:15]
	v_sub_f32_e32 v51, v61, v51
	v_add_f32_e32 v53, 1.0, v53
	v_log_f32_e32 v53, v53
	v_cndmask_b32_e64 v86, v51, v238, s[14:15]
	v_max_f32_e32 v51, 0, v62
	v_add_f32_e32 v51, v51, v53
	v_add_u32_e32 v53, -7, v67
	v_cmp_ge_i32_e64 s[14:15], v53, v138
	v_exp_f32_e64 v53, -|v63|
; __device__ __forceinline__ float fexp2(float x) { return __builtin_amdgcn_exp2f(x); }
; __device__ __forceinline__ float flog2(float x) { return __builtin_amdgcn_logf(x); }
; __device__ __forceinline__ void stick_block(f32x16& s, float& Rr, int t, int kbase, int h, bool diag) {
;     float u[16], gs[4], pg[4];
; #pragma unroll
;     for (int i = 0; i < 16; ++i) {
;         const float z = s[i];
;         const float sp = fmaxf(z, 0.f) + flog2(1.0f + fexp2(-fabsf(z)));
;         const int j = kbase + (i & 3) + 8 * (i >> 2) + 4 * h;
;         const bool valid = !diag || (j < t);
;         u[i] = valid ? -sp : 0.f;
;         s[i] = valid ? (z - sp) : -__builtin_inff();
;     }
; #pragma unroll
;     for (int c = 0; c < 4; ++c) { gs[c] = (u[4 * c] + u[4 * c + 1]) + (u[4 * c + 2] + u[4 * c + 3]); pg[c] = __shfl_xor(gs[c], 32); }
;     float run = Rr;
; #pragma unroll
;     for (int c = 3; c >= 0; --c) {
;         float tl = run + ((h == 0) ? pg[c] : 0.f);
; #pragma unroll
;     ...
;         run += gs[c] + pg[c];
;     }
;     Rr = run;
	s_and_b64 s[14:15], vcc, s[14:15]
	v_cndmask_b32_e64 v55, -v51, 0, s[14:15]
	v_sub_f32_e32 v51, v62, v51
	v_add_f32_e32 v53, 1.0, v53
	v_log_f32_e32 v53, v53
	v_cndmask_b32_e64 v87, v51, v238, s[14:15]
	v_max_f32_e32 v51, 0, v63
	v_add_f32_e32 v51, v51, v53
	v_add_u32_e32 v53, -6, v67
	v_cmp_ge_i32_e64 s[14:15], v53, v138
	v_exp_f32_e64 v53, -|v64|
	s_and_b64 s[14:15], vcc, s[14:15]
	v_cndmask_b32_e64 v88, -v51, 0, s[14:15]
	v_sub_f32_e32 v51, v63, v51
	v_add_f32_e32 v53, 1.0, v53
	v_log_f32_e32 v53, v53
	v_cndmask_b32_e64 v89, v51, v238, s[14:15]
	v_max_f32_e32 v51, 0, v64
	v_add_f32_e32 v51, v51, v53
	v_add_u32_e32 v53, -5, v67
	v_cmp_ge_i32_e64 s[14:15], v53, v138
	v_exp_f32_e64 v53, -|v65|
	s_and_b64 s[14:15], vcc, s[14:15]
	v_cndmask_b32_e64 v90, -v51, 0, s[14:15]
	v_sub_f32_e32 v51, v64, v51
	v_add_f32_e32 v53, 1.0, v53
	v_log_f32_e32 v53, v53
	v_cndmask_b32_e64 v63, v51, v238, s[14:15]
	v_max_f32_e32 v51, 0, v65
	v_add_f32_e32 v51, v51, v53
	v_add_u32_e32 v53, -4, v67
	v_cmp_ge_i32_e64 s[14:15], v53, v138
	s_and_b64 s[14:15], vcc, s[14:15]
	v_and_b32_e32 v53, 64, v236
	v_cndmask_b32_e64 v64, -v51, 0, s[14:15]
	v_sub_f32_e32 v51, v65, v51
	v_cndmask_b32_e64 v62, v51, v238, s[14:15]
	v_xor_b32_e32 v51, 32, v236
	v_add_u32_e32 v53, 64, v53
	v_cmp_lt_i32_e64 s[14:15], v51, v53
	v_add_f32_e32 v57, v75, v52
	v_add_f32_e32 v60, v80, v83
	v_cndmask_b32_e64 v51, v236, v51, s[14:15]
	v_add_f32_e32 v91, v57, v60
	v_add_f32_e32 v55, v55, v88
	v_add_f32_e32 v57, v90, v64
	v_lshlrev_b32_e32 v82, 2, v51
	v_pk_add_f32 v[54:55], v[54:55], v[56:57]
	ds_bpermute_b32 v61, v82, v55
	v_add_f32_e32 v60, v76, v85
	ds_bpermute_b32 v92, v82, v91
	v_add_f32_e32 v51, v74, v68
	v_cmp_ge_i32_e64 s[14:15], v81, v138
	s_waitcnt lgkmcnt(1)
	v_pk_add_f32 v[54:55], v[54:55], v[60:61]
	v_cndmask_b32_e64 v57, 0, v61, s[12:13]
	ds_bpermute_b32 v132, v82, v54
	v_add_f32_e32 v57, v133, v57
	v_add_f32_e32 v60, v62, v57
	v_add_f32_e32 v57, v64, v57
	v_exp_f32_e32 v62, v60
	v_add_f32_e32 v60, v63, v57
	v_add_f32_e32 v57, v90, v57
	v_exp_f32_e32 v63, v60
	v_add_f32_e32 v60, v89, v57
	v_add_f32_e32 v57, v88, v57
	v_add_f32_e32 v57, v87, v57
	v_exp_f32_e32 v65, v57
	s_waitcnt lgkmcnt(0)
	v_cndmask_b32_e64 v57, 0, v132, s[12:13]
	v_pk_add_f32 v[54:55], v[54:55], v[132:133]
	v_exp_f32_e32 v64, v60
	v_add_f32_e32 v57, v57, v55
	v_add_f32_e32 v60, v86, v57
	v_add_f32_e32 v57, v85, v57
	v_exp_f32_e32 v74, v60
	v_add_f32_e32 v60, v77, v57
	v_add_f32_e32 v57, v76, v57
	v_add_f32_e32 v59, v59, v57
	v_add_f32_e32 v56, v56, v57
	v_exp_f32_e32 v76, v59
	v_add_f32_e32 v56, v58, v56
	v_pk_add_f32 v[58:59], v[54:55], v[54:55] op_sel:[0,1] op_sel_hi:[1,0]
	v_cndmask_b32_e64 v54, 0, v92, s[12:13]
	v_add_f32_e32 v54, v54, v58
	v_add_f32_e32 v55, v84, v54
	v_add_f32_e32 v54, v83, v54
	v_exp_f32_e32 v59, v55
	v_add_f32_e32 v55, v78, v54
	v_add_f32_e32 v54, v80, v54
	v_add_f32_e32 v52, v52, v54
	v_add_f32_e32 v50, v50, v52
	v_exp_f32_e64 v52, -|v34|
	v_exp_f32_e32 v80, v50
	v_max_f32_e32 v50, 0, v34
	v_add_f32_e32 v52, 1.0, v52
	v_log_f32_e32 v52, v52
	s_and_b64 s[14:15], vcc, s[14:15]
	v_exp_f32_e32 v77, v56
	v_exp_f32_e32 v75, v60
	v_add_f32_e32 v50, v50, v52
	v_cndmask_b32_e64 v56, -v50, 0, s[14:15]
	v_sub_f32_e32 v34, v34, v50
	v_exp_f32_e64 v50, -|v35|
	v_cndmask_b32_e64 v81, v34, v238, s[14:15]
	v_max_f32_e32 v34, 0, v35
	v_add_f32_e32 v50, 1.0, v50
	v_log_f32_e32 v50, v50
	v_exp_f32_e32 v78, v55
	v_add_f32_e32 v55, v79, v54
	v_exp_f32_e32 v79, v55
	v_add_f32_e32 v50, v34, v50
	v_subrev_u32_e32 v34, 62, v67
	v_cmp_ge_i32_e64 s[14:15], v34, v138
	s_and_b64 s[14:15], vcc, s[14:15]
	v_sub_f32_e32 v35, v35, v50
	v_cndmask_b32_e64 v34, -v50, 0, s[14:15]
	v_exp_f32_e64 v50, -|v36|
	v_cndmask_b32_e64 v83, v35, v238, s[14:15]
	v_max_f32_e32 v35, 0, v36
	v_add_f32_e32 v50, 1.0, v50
	v_log_f32_e32 v50, v50
	v_add_f32_e32 v55, v91, v92
	v_add_f32_e32 v53, v70, v72
	v_add_f32_e32 v53, v51, v53
	v_add_f32_e32 v35, v35, v50
	v_subrev_u32_e32 v50, 61, v67
	v_cmp_ge_i32_e64 s[14:15], v50, v138
	s_and_b64 s[14:15], vcc, s[14:15]
	v_exp_f32_e64 v50, -|v39|
	v_cndmask_b32_e64 v60, -v35, 0, s[14:15]
	v_sub_f32_e32 v35, v36, v35
	v_exp_f32_e64 v36, -|v37|
	v_cndmask_b32_e64 v84, v35, v238, s[14:15]
	v_max_f32_e32 v35, 0, v37
	v_add_f32_e32 v36, 1.0, v36
	v_log_f32_e32 v36, v36
	v_add_f32_e32 v50, 1.0, v50
	v_log_f32_e32 v50, v50
	ds_bpermute_b32 v51, v82, v53
	v_add_f32_e32 v35, v35, v36
	v_subrev_u32_e32 v36, 60, v67
	v_cmp_ge_i32_e64 s[14:15], v36, v138
	s_and_b64 s[14:15], vcc, s[14:15]
	s_waitcnt lgkmcnt(0)
; __device__ __forceinline__ float fexp2(float x) { return __builtin_amdgcn_exp2f(x); }
; __device__ __forceinline__ float flog2(float x) { return __builtin_amdgcn_logf(x); }
; __device__ __forceinline__ void stick_block(f32x16& s, float& Rr, int t, int kbase, int h, bool diag) {
;     float u[16], gs[4], pg[4];
; #pragma unroll
;     for (int i = 0; i < 16; ++i) {
;         const float z = s[i];
;         const float sp = fmaxf(z, 0.f) + flog2(1.0f + fexp2(-fabsf(z)));
;         const int j = kbase + (i & 3) + 8 * (i >> 2) + 4 * h;
;         const bool valid = !diag || (j < t);
;         u[i] = valid ? -sp : 0.f;
;         s[i] = valid ? (z - sp) : -__builtin_inff();
;     }
; #pragma unroll
;     for (int c = 0; c < 4; ++c) { gs[c] = (u[4 * c] + u[4 * c + 1]) + (u[4 * c + 2] + u[4 * c + 3]); pg[c] = __shfl_xor(gs[c], 32); }
	v_cndmask_b32_e64 v61, 0, v51, s[12:13]
	v_cndmask_b32_e64 v36, -v35, 0, s[14:15]
	v_sub_f32_e32 v35, v37, v35
	v_exp_f32_e64 v37, -|v38|
	v_cndmask_b32_e64 v85, v35, v238, s[14:15]
	v_max_f32_e32 v35, 0, v38
	v_add_f32_e32 v37, 1.0, v37
	v_log_f32_e32 v37, v37
	s_nop 0
	v_add_f32_e32 v37, v35, v37
	v_subrev_u32_e32 v35, 55, v67
	v_cmp_ge_i32_e64 s[14:15], v35, v138
	s_and_b64 s[14:15], vcc, s[14:15]
	s_nop 0
	v_cndmask_b32_e64 v35, -v37, 0, s[14:15]
	v_sub_f32_e32 v37, v38, v37
	v_cndmask_b32_e64 v38, v37, v238, s[14:15]
	v_max_f32_e32 v37, 0, v39
	v_add_f32_e32 v37, v37, v50
	v_subrev_u32_e32 v50, 54, v67
	v_cmp_ge_i32_e64 s[14:15], v50, v138
	v_exp_f32_e64 v50, -|v40|
	s_and_b64 s[14:15], vcc, s[14:15]
	v_cndmask_b32_e64 v86, -v37, 0, s[14:15]
	v_sub_f32_e32 v37, v39, v37
	v_add_f32_e32 v50, 1.0, v50
	v_log_f32_e32 v50, v50
	v_cndmask_b32_e64 v39, v37, v238, s[14:15]
	v_max_f32_e32 v37, 0, v40
	v_add_f32_e32 v37, v37, v50
	v_subrev_u32_e32 v50, 53, v67
	v_cmp_ge_i32_e64 s[14:15], v50, v138
	v_exp_f32_e64 v50, -|v41|
	s_and_b64 s[14:15], vcc, s[14:15]
	v_cndmask_b32_e64 v87, -v37, 0, s[14:15]
	v_sub_f32_e32 v37, v40, v37
	v_add_f32_e32 v50, 1.0, v50
	v_log_f32_e32 v50, v50
	v_cndmask_b32_e64 v40, v37, v238, s[14:15]
	v_max_f32_e32 v37, 0, v41
	v_add_f32_e32 v37, v37, v50
	v_subrev_u32_e32 v50, 52, v67
	v_cmp_ge_i32_e64 s[14:15], v50, v138
	v_exp_f32_e64 v50, -|v42|
	s_and_b64 s[14:15], vcc, s[14:15]
	v_cndmask_b32_e64 v88, -v37, 0, s[14:15]
	v_sub_f32_e32 v37, v41, v37
	v_add_f32_e32 v50, 1.0, v50
	v_log_f32_e32 v50, v50
	v_cndmask_b32_e64 v41, v37, v238, s[14:15]
	v_max_f32_e32 v37, 0, v42
	v_add_f32_e32 v37, v37, v50
	v_subrev_u32_e32 v50, 47, v67
	v_cmp_ge_i32_e64 s[14:15], v50, v138
	v_exp_f32_e64 v50, -|v43|
	s_and_b64 s[14:15], vcc, s[14:15]
	v_cndmask_b32_e64 v89, -v37, 0, s[14:15]
	v_sub_f32_e32 v37, v42, v37
	v_add_f32_e32 v50, 1.0, v50
	v_log_f32_e32 v50, v50
	v_cndmask_b32_e64 v42, v37, v238, s[14:15]
	v_max_f32_e32 v37, 0, v43
	v_add_f32_e32 v37, v37, v50
	v_subrev_u32_e32 v50, 46, v67
	v_cmp_ge_i32_e64 s[14:15], v50, v138
	v_exp_f32_e64 v50, -|v44|
	s_and_b64 s[14:15], vcc, s[14:15]
	v_cndmask_b32_e64 v90, -v37, 0, s[14:15]
	v_sub_f32_e32 v37, v43, v37
	v_add_f32_e32 v50, 1.0, v50
	v_log_f32_e32 v50, v50
	v_cndmask_b32_e64 v43, v37, v238, s[14:15]
	v_max_f32_e32 v37, 0, v44
	v_add_f32_e32 v37, v37, v50
	v_subrev_u32_e32 v50, 45, v67
	v_cmp_ge_i32_e64 s[14:15], v50, v138
	s_and_b64 s[14:15], vcc, s[14:15]
	v_add_f32_e32 v35, v35, v86
	v_cndmask_b32_e64 v91, -v37, 0, s[14:15]
	v_sub_f32_e32 v37, v44, v37
	v_exp_f32_e64 v44, -|v45|
	v_cndmask_b32_e64 v92, v37, v238, s[14:15]
	v_max_f32_e32 v37, 0, v45
	v_add_f32_e32 v44, 1.0, v44
	v_log_f32_e32 v44, v44
	s_nop 0
	v_add_f32_e32 v37, v37, v44
	v_subrev_u32_e32 v44, 44, v67
	v_cmp_ge_i32_e64 s[14:15], v44, v138
	v_exp_f32_e64 v44, -|v46|
	s_and_b64 s[14:15], vcc, s[14:15]
	v_cndmask_b32_e64 v93, -v37, 0, s[14:15]
	v_sub_f32_e32 v37, v45, v37
	v_exp_f32_e64 v45, -|v47|
	v_add_f32_e32 v44, 1.0, v44
	v_log_f32_e32 v44, v44
	v_cndmask_b32_e64 v94, v37, v238, s[14:15]
	v_add_f32_e32 v45, 1.0, v45
	v_max_f32_e32 v37, 0, v46
	v_log_f32_e32 v45, v45
	v_add_f32_e32 v37, v37, v44
	v_subrev_u32_e32 v44, 39, v67
	v_cmp_ge_i32_e64 s[14:15], v44, v138
	s_and_b64 s[14:15], vcc, s[14:15]
	v_max_f32_e32 v44, 0, v47
	v_cndmask_b32_e64 v52, -v37, 0, s[14:15]
	v_sub_f32_e32 v37, v46, v37
	v_add_f32_e32 v44, v44, v45
	v_subrev_u32_e32 v45, 38, v67
	v_cndmask_b32_e64 v37, v37, v238, s[14:15]
	v_cmp_ge_i32_e64 s[14:15], v45, v138
	v_exp_f32_e64 v45, -|v48|
	s_and_b64 s[14:15], vcc, s[14:15]
	v_cndmask_b32_e64 v50, -v44, 0, s[14:15]
	v_sub_f32_e32 v44, v47, v44
	v_add_f32_e32 v45, 1.0, v45
	v_log_f32_e32 v45, v45
	v_cndmask_b32_e64 v95, v44, v238, s[14:15]
	v_max_f32_e32 v44, 0, v48
	v_add_f32_e32 v44, v44, v45
	v_subrev_u32_e32 v45, 37, v67
	v_cmp_ge_i32_e64 s[14:15], v45, v138
	v_exp_f32_e64 v45, -|v49|
	s_and_b64 s[14:15], vcc, s[14:15]
	v_cndmask_b32_e64 v54, -v44, 0, s[14:15]
	v_sub_f32_e32 v44, v48, v44
	v_add_f32_e32 v45, 1.0, v45
	v_log_f32_e32 v45, v45
	v_cndmask_b32_e64 v96, v44, v238, s[14:15]
	v_max_f32_e32 v44, 0, v49
	v_add_f32_e32 v45, v44, v45
	v_subrev_u32_e32 v44, 36, v67
	v_cmp_ge_i32_e64 s[14:15], v44, v138
	s_and_b64 vcc, vcc, s[14:15]
	v_cndmask_b32_e64 v44, -v45, 0, vcc
	v_sub_f32_e32 v45, v49, v45
	v_cndmask_b32_e32 v67, v45, v238, vcc
	v_add_f32_e32 v45, v87, v88
	v_add_f32_e32 v57, v35, v45
	v_add_f32_e32 v45, v89, v90
	v_add_f32_e32 v46, v91, v93
	v_add_f32_e32 v89, v45, v46
	v_mov_b32_e32 v45, v58
	v_pk_add_f32 v[46:47], v[54:55], v[44:45]
	ds_bpermute_b32 v97, v82, v89
	v_add_f32_e32 v45, v61, v47
	v_add_f32_e32 v48, v73, v45
	v_add_f32_e32 v45, v72, v45
	v_exp_f32_e32 v55, v48
	v_add_f32_e32 v48, v71, v45
	v_add_f32_e32 v45, v70, v45
	v_exp_f32_e32 v58, v48
	v_add_f32_e32 v48, v69, v45
	v_exp_f32_e32 v69, v48
	v_add_f32_e32 v45, v68, v45
	v_pk_add_f32 v[48:49], v[52:53], v[50:51]
	v_add_f32_e32 v45, v66, v45
	v_pk_add_f32 v[46:47], v[48:49], v[46:47]
	v_exp_f32_e32 v66, v45
	ds_bpermute_b32 v45, v82, v46
	ds_bpermute_b32 v35, v82, v57
	s_waitcnt lgkmcnt(2)
; #define LAS __attribute__((address_space(3)))
; #define MFMA32(a, b, c) __builtin_amdgcn_mfma_f32_32x32x16_bf16((a), (b), (c), 0, 0, 0)
; __device__ __forceinline__ void stick_block(f32x16& s, float& Rr, int t, int kbase, int h, bool diag) {
;     ...
;     for (int c = 0; c < 4; ++c) { gs[c] = (u[4 * c] + u[4 * c + 1]) + (u[4 * c + 2] + u[4 * c + 3]); pg[c] = __shfl_xor(gs[c], 32); }
;     float run = Rr;
; #pragma unroll
;     for (int c = 3; c >= 0; --c) {
;         float tl = run + ((h == 0) ? pg[c] : 0.f);
; #pragma unroll
;     ...
;         run += gs[c] + pg[c];
;     }
;     Rr = run;
; __device__ __forceinline__ void pv_tile(LAS unsigned char* vt, const f32x16& s0, const f32x16& s1, int h, int lane, f32x16 (&o)[2]) {
; #pragma unroll
;     for (int st = 0; st < 2; ++st) {
;         const bf16x8 pb = pack8(s0, st);
; #pragma unroll
;         for (int db = 0; db < 2; ++db) o[db] = MFMA32(vfrag<64>(vt, 32 * db, 16 * st + 4 * h, lane), pb, o[db]);
;     }
; #pragma unroll
;     for (int st = 0; st < 2; ++st) {
;         const bf16x8 pb = pack8(s1, st);
; #pragma unroll
;         for (int db = 0; db < 2; ++db) o[db] = MFMA32(vfrag<64>(vt, 32 * db, 32 + 16 * st + 4 * h, lane), pb, o[db]);
;     }
	v_add_f32_e32 v61, v89, v97
	s_waitcnt lgkmcnt(1)
	v_cndmask_b32_e64 v48, 0, v45, s[12:13]
	v_add_f32_e32 v48, v48, v47
	v_add_f32_e32 v44, v44, v48
	v_add_f32_e32 v49, v67, v48
	v_add_f32_e32 v48, v96, v44
	v_add_f32_e32 v44, v54, v44
	v_add_f32_e32 v51, v95, v44
	v_add_f32_e32 v44, v50, v44
	v_add_f32_e32 v37, v37, v44
	v_exp_f32_e32 v50, v37
	v_add_f32_e32 v37, v46, v45
	v_add_f32_e32 v37, v37, v47
	v_cndmask_b32_e64 v44, 0, v97, s[12:13]
	v_add_f32_e32 v44, v44, v37
	v_add_f32_e32 v45, v94, v44
	v_add_f32_e32 v44, v93, v44
	v_exp_f32_e32 v46, v45
	v_add_f32_e32 v45, v92, v44
	v_add_f32_e32 v44, v91, v44
	v_add_f32_e32 v43, v43, v44
	v_exp_f32_e32 v52, v43
	v_add_f32_e32 v43, v90, v44
	v_add_f32_e32 v42, v42, v43
	v_exp_f32_e32 v47, v45
	v_exp_f32_e32 v53, v42
	v_pk_add_f32 v[42:43], v[60:61], v[36:37]
	s_waitcnt lgkmcnt(0)
	v_pk_add_f32 v[44:45], v[56:57], v[34:35]
	v_cndmask_b32_e64 v54, 0, v35, s[12:13]
	v_pk_add_f32 v[44:45], v[44:45], v[42:43]
	ds_bpermute_b32 v35, v82, v44
	v_add_f32_e32 v37, v54, v43
	v_add_f32_e32 v41, v41, v37
	v_add_f32_e32 v37, v88, v37
	v_add_f32_e32 v40, v40, v37
	v_add_f32_e32 v37, v87, v37
	v_add_f32_e32 v39, v39, v37
	v_add_f32_e32 v37, v86, v37
	v_add_f32_e32 v37, v38, v37
	s_waitcnt lgkmcnt(0)
	v_cndmask_b32_e64 v38, 0, v35, s[12:13]
	v_add_f32_e32 v38, v38, v45
	v_add_f32_e32 v36, v36, v38
	v_add_f32_e32 v42, v85, v38
	v_add_f32_e32 v38, v84, v36
	v_exp_f32_e32 v42, v42
	v_exp_f32_e32 v38, v38
	v_exp_f32_e32 v41, v41
	v_exp_f32_e32 v40, v40
	v_exp_f32_e32 v39, v39
	v_exp_f32_e32 v37, v37
	v_add_f32_e32 v36, v60, v36
	v_add_f32_e32 v34, v34, v36
	v_add_f32_e32 v35, v44, v35
	v_add_f32_e32 v43, v83, v36
	v_add_f32_e32 v34, v81, v34
	v_add_f32_e32 v133, v35, v45
	v_cvt_pk_bf16_f32 v35, v38, v42
	v_add_u32_e32 v42, s45, v200
	v_exp_f32_e32 v43, v43
	v_exp_f32_e32 v34, v34
	v_cvt_pk_bf16_f32 v36, v37, v39
	v_cvt_pk_bf16_f32 v37, v40, v41
	ds_read_b64_tr_b16 v[38:39], v42 offset:36864
	ds_read_b64_tr_b16 v[40:41], v42 offset:38016
	v_cvt_pk_bf16_f32 v34, v34, v43
	v_exp_f32_e32 v49, v49
	v_exp_f32_e32 v48, v48
	s_waitcnt lgkmcnt(0)
	v_mfma_f32_32x32x16_bf16 v[18:33], v[38:41], v[34:37], v[18:33]
	ds_read_b64_tr_b16 v[38:39], v42 offset:36928
	ds_read_b64_tr_b16 v[40:41], v42 offset:38080
	v_exp_f32_e32 v51, v51
	s_waitcnt lgkmcnt(0)
	v_mfma_f32_32x32x16_bf16 v[2:17], v[38:41], v[34:37], v[2:17]
	ds_read_b64_tr_b16 v[38:39], v42 offset:39168
	ds_read_b64_tr_b16 v[40:41], v42 offset:40320
	v_cvt_pk_bf16_f32 v34, v53, v52
	v_cvt_pk_bf16_f32 v35, v47, v46
	v_cvt_pk_bf16_f32 v36, v50, v51
	v_cvt_pk_bf16_f32 v37, v48, v49
	s_waitcnt lgkmcnt(0)
	s_nop 0
	v_mfma_f32_32x32x16_bf16 v[18:33], v[38:41], v[34:37], v[18:33]
	ds_read_b64_tr_b16 v[38:39], v42 offset:39232
	ds_read_b64_tr_b16 v[40:41], v42 offset:40384
	s_waitcnt lgkmcnt(0)
	v_mfma_f32_32x32x16_bf16 v[2:17], v[38:41], v[34:37], v[2:17]
	ds_read_b64_tr_b16 v[38:39], v42 offset:41472
	ds_read_b64_tr_b16 v[40:41], v42 offset:42624
	v_cvt_pk_bf16_f32 v34, v66, v69
	v_cvt_pk_bf16_f32 v35, v58, v55
	v_cvt_pk_bf16_f32 v36, v80, v79
	v_cvt_pk_bf16_f32 v37, v78, v59
	s_waitcnt lgkmcnt(0)
	s_nop 0
	v_mfma_f32_32x32x16_bf16 v[18:33], v[38:41], v[34:37], v[18:33]
	ds_read_b64_tr_b16 v[38:39], v42 offset:41536
	ds_read_b64_tr_b16 v[40:41], v42 offset:42688
	s_waitcnt lgkmcnt(0)
	v_mfma_f32_32x32x16_bf16 v[2:17], v[38:41], v[34:37], v[2:17]
	ds_read_b64_tr_b16 v[38:39], v42 offset:43776
	ds_read_b64_tr_b16 v[40:41], v42 offset:44928
	v_cvt_pk_bf16_f32 v34, v77, v76
	v_cvt_pk_bf16_f32 v35, v75, v74
	v_cvt_pk_bf16_f32 v36, v65, v64
	v_cvt_pk_bf16_f32 v37, v63, v62
	s_waitcnt lgkmcnt(0)
	s_nop 0
	v_mfma_f32_32x32x16_bf16 v[18:33], v[38:41], v[34:37], v[18:33]
	ds_read_b64_tr_b16 v[38:39], v42 offset:43840
	ds_read_b64_tr_b16 v[40:41], v42 offset:44992
	s_waitcnt lgkmcnt(0)
	v_mfma_f32_32x32x16_bf16 v[2:17], v[38:41], v[34:37], v[2:17]

; #define LAS __attribute__((address_space(3)))
; #define MFMA32(a, b, c) __builtin_amdgcn_mfma_f32_32x32x16_bf16((a), (b), (c), 0, 0, 0)
; __device__ __forceinline__ float fexp2(float x) { return __builtin_amdgcn_exp2f(x); }
; __device__ __forceinline__ float flog2(float x) { return __builtin_amdgcn_logf(x); }
; __device__ __forceinline__ void stick_block(f32x16& s, float& Rr, int t, int kbase, int h, bool diag) {
;     float u[16], gs[4], pg[4];
; #pragma unroll
;     for (int i = 0; i < 16; ++i) {
;         const float z = s[i];
;         const float sp = fmaxf(z, 0.f) + flog2(1.0f + fexp2(-fabsf(z)));
;         const int j = kbase + (i & 3) + 8 * (i >> 2) + 4 * h;
;         const bool valid = !diag || (j < t);
;         u[i] = valid ? -sp : 0.f;
;         s[i] = valid ? (z - sp) : -__builtin_inff();
; __device__ __forceinline__ void qk_tile(LAS unsigned char* ks, const bf16x8 (&qf)[4], int r, int h, f32x16& s0, f32x16& s1) {
;     bf16x8 kf[8];
; #pragma unroll
;     for (int kk = 0; kk < 4; ++kk) {
;         kf[2 * kk]     = *(const LAS bf16x8*)(ks + (r * KPITCH + 16 * kk + 8 * h) * 2);
;         kf[2 * kk + 1] = *(const LAS bf16x8*)(ks + ((32 + r) * KPITCH + 16 * kk + 8 * h) * 2);
;     }
; #pragma unroll
;     for (int i = 0; i < 16; ++i) { s0[i] = 0.f; s1[i] = 0.f; }
; #pragma unroll
;     for (int kk = 0; kk < 4; ++kk) { s0 = MFMA32(kf[2 * kk], qf[kk], s0); s1 = MFMA32(kf[2 * kk + 1], qf[kk], s1); }
; }
.LBB0_628:
	v_add_u32_e32 v132, s45, v206
	ds_read_b128 v[34:37], v132 offset:4608
	ds_read_b128 v[38:41], v132
	ds_read_b128 v[42:45], v132 offset:32
	ds_read_b128 v[46:49], v132 offset:4640
	ds_read_b128 v[50:53], v132 offset:64
	ds_read_b128 v[54:57], v132 offset:4672
	ds_read_b128 v[58:61], v132 offset:96
	ds_read_b128 v[62:65], v132 offset:4704
	s_waitcnt lgkmcnt(7)
	v_mfma_f32_32x32x16_bf16 v[82:97], v[34:37], v[98:101], 0
	v_cmp_ge_i32_e32 vcc, s36, v137
	s_waitcnt lgkmcnt(4)
	v_mfma_f32_32x32x16_bf16 v[82:97], v[46:49], v[102:105], v[82:97]
	v_mfma_f32_32x32x16_bf16 v[66:81], v[38:41], v[98:101], 0
	s_waitcnt lgkmcnt(2)
	v_mfma_f32_32x32x16_bf16 v[82:97], v[54:57], v[106:109], v[82:97]
	v_mfma_f32_32x32x16_bf16 v[66:81], v[42:45], v[102:105], v[66:81]
	s_waitcnt lgkmcnt(0)
	v_mfma_f32_32x32x16_bf16 v[82:97], v[62:65], v[110:113], v[82:97]
	v_mfma_f32_32x32x16_bf16 v[66:81], v[50:53], v[106:109], v[66:81]
	ds_read_b128 v[34:37], v132 offset:9216
	ds_read_b128 v[50:53], v132 offset:13824
	ds_read_b128 v[140:143], v132 offset:9248
	ds_read_b128 v[144:147], v132 offset:13856
	ds_read_b128 v[148:151], v132 offset:9280
	ds_read_b128 v[152:155], v132 offset:13888
	ds_read_b128 v[158:161], v132 offset:9312
	ds_read_b128 v[162:165], v132 offset:13920
	s_nop 2
	v_exp_f32_e64 v135, -|v82|
	v_max_f32_e32 v134, 0, v82
	v_add_f32_e32 v135, 1.0, v135
	v_log_f32_e32 v135, v135
	s_waitcnt lgkmcnt(7)
	v_mfma_f32_32x32x16_bf16 v[34:49], v[34:37], v[98:101], 0
	v_add_f32_e32 v135, v134, v135
	v_sub_f32_e32 v82, v82, v135
	s_waitcnt lgkmcnt(5)
	v_mfma_f32_32x32x16_bf16 v[34:49], v[140:143], v[102:105], v[34:49]
	v_add_u32_e32 v140, s36, v198
	v_subrev_u32_e32 v132, 31, v140
	v_cmp_ge_i32_e64 s[14:15], v132, v138
	v_exp_f32_e64 v132, -|v83|
	s_and_b64 s[14:15], vcc, s[14:15]
	v_cndmask_b32_e64 v142, v82, v238, s[14:15]
	v_add_f32_e32 v132, 1.0, v132
	v_log_f32_e32 v132, v132
	v_max_f32_e32 v82, 0, v83
	v_cndmask_b32_e64 v134, -v135, 0, s[14:15]
	v_mfma_f32_32x32x16_bf16 v[66:81], v[58:61], v[110:113], v[66:81]
	v_add_f32_e32 v132, v82, v132
	v_subrev_u32_e32 v82, 30, v140
	v_cmp_ge_i32_e64 s[14:15], v82, v138
	s_and_b64 s[14:15], vcc, s[14:15]
	v_sub_f32_e32 v83, v83, v132
	v_cndmask_b32_e64 v82, -v132, 0, s[14:15]
	v_exp_f32_e64 v132, -|v84|
	v_cndmask_b32_e64 v143, v83, v238, s[14:15]
	v_max_f32_e32 v83, 0, v84
	v_add_f32_e32 v132, 1.0, v132
	v_log_f32_e32 v132, v132
	v_mfma_f32_32x32x16_bf16 v[50:65], v[50:53], v[98:101], 0
	v_subrev_u32_e32 v141, 63, v140
	v_add_f32_e32 v83, v83, v132
	v_subrev_u32_e32 v132, 29, v140
	v_cmp_ge_i32_e64 s[14:15], v132, v138
	s_and_b64 s[14:15], vcc, s[14:15]
	s_nop 0
	v_cndmask_b32_e64 v132, -v83, 0, s[14:15]
	v_sub_f32_e32 v83, v84, v83
	v_exp_f32_e64 v84, -|v85|
	s_waitcnt lgkmcnt(4)
	v_mfma_f32_32x32x16_bf16 v[50:65], v[144:147], v[102:105], v[50:65]
	v_cndmask_b32_e64 v144, v83, v238, s[14:15]
	v_add_f32_e32 v84, 1.0, v84
	v_log_f32_e32 v84, v84
	v_max_f32_e32 v83, 0, v85
	v_add_f32_e32 v83, v83, v84
	v_subrev_u32_e32 v84, 28, v140
	v_cmp_ge_i32_e64 s[14:15], v84, v138
	s_and_b64 s[14:15], vcc, s[14:15]
	s_waitcnt lgkmcnt(3)
	v_mfma_f32_32x32x16_bf16 v[34:49], v[148:151], v[106:109], v[34:49]
	v_cndmask_b32_e64 v84, -v83, 0, s[14:15]
	v_sub_f32_e32 v83, v85, v83
	v_exp_f32_e64 v85, -|v86|
	v_cndmask_b32_e64 v145, v83, v238, s[14:15]
	v_max_f32_e32 v83, 0, v86
	v_add_f32_e32 v85, 1.0, v85
	v_log_f32_e32 v85, v85
	s_waitcnt lgkmcnt(2)
	v_mfma_f32_32x32x16_bf16 v[50:65], v[152:155], v[106:109], v[50:65]
	v_add_f32_e32 v85, v83, v85
	v_subrev_u32_e32 v83, 23, v140
	v_cmp_ge_i32_e64 s[14:15], v83, v138
	s_and_b64 s[14:15], vcc, s[14:15]
	s_nop 0
	v_cndmask_b32_e64 v83, -v85, 0, s[14:15]
	v_sub_f32_e32 v85, v86, v85
	v_exp_f32_e64 v86, -|v87|
	v_cndmask_b32_e64 v146, v85, v238, s[14:15]
	v_max_f32_e32 v85, 0, v87
	v_add_f32_e32 v86, 1.0, v86
	v_log_f32_e32 v86, v86
	s_waitcnt lgkmcnt(1)
	v_mfma_f32_32x32x16_bf16 v[34:49], v[158:161], v[110:113], v[34:49]
	v_add_f32_e32 v85, v85, v86
	v_subrev_u32_e32 v86, 22, v140
	v_cmp_ge_i32_e64 s[14:15], v86, v138
	v_exp_f32_e64 v86, -|v88|
	s_and_b64 s[14:15], vcc, s[14:15]
	v_cndmask_b32_e64 v147, -v85, 0, s[14:15]
	v_sub_f32_e32 v85, v87, v85
	v_add_f32_e32 v86, 1.0, v86
	v_log_f32_e32 v86, v86
	v_cndmask_b32_e64 v148, v85, v238, s[14:15]
	v_max_f32_e32 v85, 0, v88
	v_add_f32_e32 v85, v85, v86
	v_subrev_u32_e32 v86, 21, v140
	v_cmp_ge_i32_e64 s[14:15], v86, v138
	v_exp_f32_e64 v86, -|v89|
	s_and_b64 s[14:15], vcc, s[14:15]
	v_cndmask_b32_e64 v149, -v85, 0, s[14:15]
	v_sub_f32_e32 v85, v88, v85
	v_add_f32_e32 v86, 1.0, v86
	v_log_f32_e32 v86, v86
	v_cndmask_b32_e64 v150, v85, v238, s[14:15]
	v_max_f32_e32 v85, 0, v89
	v_add_f32_e32 v85, v85, v86
	v_subrev_u32_e32 v86, 20, v140
	v_cmp_ge_i32_e64 s[14:15], v86, v138
	v_exp_f32_e64 v86, -|v90|
	s_and_b64 s[14:15], vcc, s[14:15]
	v_cndmask_b32_e64 v151, -v85, 0, s[14:15]
	v_sub_f32_e32 v85, v89, v85
	v_add_f32_e32 v86, 1.0, v86
	v_log_f32_e32 v86, v86
	v_cndmask_b32_e64 v152, v85, v238, s[14:15]
	v_max_f32_e32 v85, 0, v90
	v_add_f32_e32 v85, v85, v86
	v_add_u32_e32 v86, -15, v140
	v_cmp_ge_i32_e64 s[14:15], v86, v138
	v_exp_f32_e64 v86, -|v91|
	s_and_b64 s[14:15], vcc, s[14:15]
	v_cndmask_b32_e64 v87, -v85, 0, s[14:15]
	v_sub_f32_e32 v85, v90, v85
	v_add_f32_e32 v86, 1.0, v86
	v_log_f32_e32 v86, v86
	v_cndmask_b32_e64 v153, v85, v238, s[14:15]
	v_max_f32_e32 v85, 0, v91
	v_add_f32_e32 v85, v85, v86
	v_add_u32_e32 v86, -14, v140
	v_cmp_ge_i32_e64 s[14:15], v86, v138
	v_exp_f32_e64 v86, -|v92|
	s_and_b64 s[14:15], vcc, s[14:15]
	v_cndmask_b32_e64 v154, -v85, 0, s[14:15]
	v_sub_f32_e32 v85, v91, v85
	v_add_f32_e32 v86, 1.0, v86
; __device__ __forceinline__ float fexp2(float x) { return __builtin_amdgcn_exp2f(x); }
; __device__ __forceinline__ float flog2(float x) { return __builtin_amdgcn_logf(x); }
; __device__ __forceinline__ void stick_block(f32x16& s, float& Rr, int t, int kbase, int h, bool diag) {
;     float u[16], gs[4], pg[4];
; #pragma unroll
;     for (int i = 0; i < 16; ++i) {
;         const float z = s[i];
;         const float sp = fmaxf(z, 0.f) + flog2(1.0f + fexp2(-fabsf(z)));
;         const int j = kbase + (i & 3) + 8 * (i >> 2) + 4 * h;
;         const bool valid = !diag || (j < t);
;         u[i] = valid ? -sp : 0.f;
;         s[i] = valid ? (z - sp) : -__builtin_inff();
;     }
; #pragma unroll
;     for (int c = 0; c < 4; ++c) { gs[c] = (u[4 * c] + u[4 * c + 1]) + (u[4 * c + 2] + u[4 * c + 3]); pg[c] = __shfl_xor(gs[c], 32); }
;     float run = Rr;
; #pragma unroll
;     for (int c = 3; c >= 0; --c) {
;         float tl = run + ((h == 0) ? pg[c] : 0.f);
; #pragma unroll
;     ...
;         run += gs[c] + pg[c];
;     }
;     Rr = run;
	v_log_f32_e32 v86, v86
	v_cndmask_b32_e64 v155, v85, v238, s[14:15]
	v_max_f32_e32 v85, 0, v92
	v_add_f32_e32 v85, v85, v86
	v_add_u32_e32 v86, -13, v140
	v_cmp_ge_i32_e64 s[14:15], v86, v138
	v_exp_f32_e64 v86, -|v93|
	s_and_b64 s[14:15], vcc, s[14:15]
	v_cndmask_b32_e64 v158, -v85, 0, s[14:15]
	v_sub_f32_e32 v85, v92, v85
	v_add_f32_e32 v86, 1.0, v86
	v_log_f32_e32 v86, v86
	v_cndmask_b32_e64 v92, v85, v238, s[14:15]
	v_max_f32_e32 v85, 0, v93
	v_add_f32_e32 v85, v85, v86
	v_add_u32_e32 v86, -12, v140
	v_cmp_ge_i32_e64 s[14:15], v86, v138
	v_exp_f32_e64 v86, -|v94|
	v_exp_f32_e64 v89, -|v95|
	s_and_b64 s[14:15], vcc, s[14:15]
	v_cndmask_b32_e64 v159, -v85, 0, s[14:15]
	v_add_f32_e32 v86, 1.0, v86
	v_log_f32_e32 v86, v86
	v_sub_f32_e32 v85, v93, v85
	v_cndmask_b32_e64 v91, v85, v238, s[14:15]
	v_add_f32_e32 v89, 1.0, v89
	v_max_f32_e32 v85, 0, v94
	v_log_f32_e32 v89, v89
	v_add_f32_e32 v85, v85, v86
	v_add_u32_e32 v86, -7, v140
	v_exp_f32_e64 v93, -|v96|
	v_cmp_ge_i32_e64 s[14:15], v86, v138
	s_and_b64 s[14:15], vcc, s[14:15]
	v_max_f32_e32 v86, 0, v95
	v_cndmask_b32_e64 v88, -v85, 0, s[14:15]
	v_sub_f32_e32 v85, v94, v85
	v_add_f32_e32 v86, v86, v89
	v_add_u32_e32 v89, -6, v140
	v_cndmask_b32_e64 v85, v85, v238, s[14:15]
	v_cmp_ge_i32_e64 s[14:15], v89, v138
	v_add_f32_e32 v93, 1.0, v93
	s_and_b64 s[14:15], vcc, s[14:15]
	v_log_f32_e32 v93, v93
	v_cndmask_b32_e64 v90, -v86, 0, s[14:15]
	v_sub_f32_e32 v86, v95, v86
	v_exp_f32_e64 v95, -|v97|
	v_cndmask_b32_e64 v89, v86, v238, s[14:15]
	v_max_f32_e32 v86, 0, v96
	v_add_f32_e32 v86, v86, v93
	v_add_u32_e32 v93, -5, v140
	v_cmp_ge_i32_e64 s[14:15], v93, v138
	v_add_f32_e32 v95, 1.0, v95
	s_and_b64 s[14:15], vcc, s[14:15]
	v_log_f32_e32 v95, v95
	v_cndmask_b32_e64 v93, -v86, 0, s[14:15]
	v_sub_f32_e32 v86, v96, v86
	v_cndmask_b32_e64 v94, v86, v238, s[14:15]
	v_max_f32_e32 v86, 0, v97
	v_add_f32_e32 v86, v86, v95
	v_add_u32_e32 v95, -4, v140
	v_cmp_ge_i32_e64 s[14:15], v95, v138
	s_and_b64 s[14:15], vcc, s[14:15]
	v_add_f32_e32 v83, v83, v147
	v_cndmask_b32_e64 v95, -v86, 0, s[14:15]
	v_sub_f32_e32 v86, v97, v86
	v_and_b32_e32 v97, 64, v236
	v_cndmask_b32_e64 v96, v86, v238, s[14:15]
	v_xor_b32_e32 v86, 32, v236
	v_add_u32_e32 v97, 64, v97
	v_cmp_lt_i32_e64 s[14:15], v86, v97
	v_add_f32_e32 v97, v149, v151
	v_add_f32_e32 v135, v83, v97
	v_add_f32_e32 v87, v87, v154
	v_add_f32_e32 v97, v158, v159
	v_cndmask_b32_e64 v86, v236, v86, s[14:15]
	v_add_f32_e32 v97, v87, v97
	v_add_f32_e32 v87, v88, v90
	v_add_f32_e32 v88, v93, v95
	v_lshlrev_b32_e32 v86, 2, v86
	v_add_f32_e32 v161, v87, v88
	s_waitcnt lgkmcnt(0)
	v_mfma_f32_32x32x16_bf16 v[50:65], v[162:165], v[110:113], v[50:65]
	ds_bpermute_b32 v162, v86, v161
	ds_bpermute_b32 v160, v86, v97
	ds_bpermute_b32 v83, v86, v135
	v_cmp_ge_i32_e64 s[14:15], v141, v138
	s_and_b64 s[14:15], vcc, s[14:15]
	s_waitcnt lgkmcnt(2)
	v_cndmask_b32_e64 v87, 0, v162, s[12:13]
	v_add_f32_e32 v88, v133, v87
	v_add_f32_e32 v95, v95, v88
	v_add_f32_e32 v93, v93, v95
	v_add_f32_e32 v90, v90, v93
	v_add_f32_e32 v85, v85, v90
	v_exp_f32_e32 v90, v85
	v_add_f32_e32 v85, v161, v162
	v_add_f32_e32 v89, v89, v93
	v_add_f32_e32 v85, v133, v85
	s_waitcnt lgkmcnt(1)
	v_cndmask_b32_e64 v93, 0, v160, s[12:13]
	v_add_f32_e32 v93, v93, v85
	v_add_f32_e32 v91, v91, v93
	v_add_f32_e32 v93, v159, v93
	v_add_f32_e32 v133, v97, v160
	v_add_f32_e32 v87, v96, v88
	v_add_f32_e32 v88, v94, v95
	v_add_f32_e32 v94, v158, v93
	v_pk_add_f32 v[96:97], v[132:133], v[84:85]
	s_waitcnt lgkmcnt(0)
	v_pk_add_f32 v[134:135], v[134:135], v[82:83]
	v_add_f32_e32 v92, v92, v93
	v_add_f32_e32 v93, v155, v94
	v_add_f32_e32 v94, v154, v94
	v_pk_add_f32 v[154:155], v[134:135], v[96:97]
	v_cndmask_b32_e64 v95, 0, v83, s[12:13]
	ds_bpermute_b32 v83, v86, v154
	v_exp_f32_e64 v135, -|v66|
	v_add_f32_e32 v95, v95, v97
	v_add_f32_e32 v96, v151, v95
	v_add_f32_e32 v97, v149, v96
	s_waitcnt lgkmcnt(0)
	v_cndmask_b32_e64 v133, 0, v83, s[12:13]
	v_add_f32_e32 v134, v133, v155
	v_add_f32_e32 v133, v145, v134
	v_add_f32_e32 v134, v84, v134
	v_add_f32_e32 v84, v144, v134
	v_add_f32_e32 v134, v132, v134
	v_add_f32_e32 v82, v82, v134
	v_add_f32_e32 v135, 1.0, v135
	v_add_f32_e32 v82, v142, v82
	v_log_f32_e32 v135, v135
	v_add_f32_e32 v132, v143, v134
	v_exp_f32_e32 v134, v82
	v_add_f32_e32 v82, v154, v83
	v_add_f32_e32 v83, v82, v155
	v_max_f32_e32 v82, 0, v66
	v_add_f32_e32 v82, v82, v135
	v_cndmask_b32_e64 v145, -v82, 0, s[14:15]
	v_sub_f32_e32 v66, v66, v82
	v_exp_f32_e64 v82, -|v67|
	v_cndmask_b32_e64 v135, v66, v238, s[14:15]
	v_max_f32_e32 v66, 0, v67
	v_add_f32_e32 v82, 1.0, v82
	v_log_f32_e32 v82, v82
	v_add_f32_e32 v85, v152, v95
	v_add_f32_e32 v95, v150, v96
	v_add_f32_e32 v96, v148, v97
	v_add_f32_e32 v66, v66, v82
	v_subrev_u32_e32 v82, 62, v140
	v_cmp_ge_i32_e64 s[14:15], v82, v138
	s_and_b64 s[14:15], vcc, s[14:15]
	v_add_f32_e32 v97, v147, v97
	v_cndmask_b32_e64 v141, -v66, 0, s[14:15]
	v_sub_f32_e32 v66, v67, v66
	v_exp_f32_e64 v67, -|v68|
	v_cndmask_b32_e64 v142, v66, v238, s[14:15]
	v_max_f32_e32 v66, 0, v68
	v_add_f32_e32 v67, 1.0, v67
	v_log_f32_e32 v67, v67
	v_add_f32_e32 v97, v146, v97
	v_add_f32_e32 v94, v153, v94
	v_exp_f32_e64 v155, -|v81|
	v_add_f32_e32 v66, v66, v67
	v_subrev_u32_e32 v67, 61, v140
	v_cmp_ge_i32_e64 s[14:15], v67, v138
	v_exp_f32_e64 v67, -|v69|
	s_and_b64 s[14:15], vcc, s[14:15]
	v_cndmask_b32_e64 v143, -v66, 0, s[14:15]
	v_sub_f32_e32 v66, v68, v66
	v_add_f32_e32 v67, 1.0, v67
	v_log_f32_e32 v67, v67
	v_cndmask_b32_e64 v144, v66, v238, s[14:15]
	v_max_f32_e32 v66, 0, v69
	v_add_f32_e32 v66, v66, v67
	v_subrev_u32_e32 v67, 60, v140
	v_cmp_ge_i32_e64 s[14:15], v67, v138
; __device__ __forceinline__ float fexp2(float x) { return __builtin_amdgcn_exp2f(x); }
; __device__ __forceinline__ float flog2(float x) { return __builtin_amdgcn_logf(x); }
; __device__ __forceinline__ void stick_block(f32x16& s, float& Rr, int t, int kbase, int h, bool diag) {
;     float u[16], gs[4], pg[4];
; #pragma unroll
;     for (int i = 0; i < 16; ++i) {
;         const float z = s[i];
;         const float sp = fmaxf(z, 0.f) + flog2(1.0f + fexp2(-fabsf(z)));
;         const int j = kbase + (i & 3) + 8 * (i >> 2) + 4 * h;
;         const bool valid = !diag || (j < t);
;         u[i] = valid ? -sp : 0.f;
;         s[i] = valid ? (z - sp) : -__builtin_inff();
;     }
; #pragma unroll
;     for (int c = 0; c < 4; ++c) { gs[c] = (u[4 * c] + u[4 * c + 1]) + (u[4 * c + 2] + u[4 * c + 3]); pg[c] = __shfl_xor(gs[c], 32); }
	v_exp_f32_e64 v67, -|v70|
	s_and_b64 s[14:15], vcc, s[14:15]
	v_cndmask_b32_e64 v146, -v66, 0, s[14:15]
	v_sub_f32_e32 v66, v69, v66
	v_add_f32_e32 v67, 1.0, v67
	v_log_f32_e32 v67, v67
	v_exp_f32_e64 v68, -|v71|
	v_cndmask_b32_e64 v147, v66, v238, s[14:15]
	v_max_f32_e32 v66, 0, v70
	v_add_f32_e32 v67, v66, v67
	v_subrev_u32_e32 v66, 55, v140
	v_cmp_ge_i32_e64 s[14:15], v66, v138
	v_add_f32_e32 v68, 1.0, v68
	s_and_b64 s[14:15], vcc, s[14:15]
	v_log_f32_e32 v68, v68
	v_cndmask_b32_e64 v66, -v67, 0, s[14:15]
	v_sub_f32_e32 v67, v70, v67
	v_exp_f32_e64 v69, -|v72|
	v_cndmask_b32_e64 v148, v67, v238, s[14:15]
	v_max_f32_e32 v67, 0, v71
	v_add_f32_e32 v67, v67, v68
	v_subrev_u32_e32 v68, 54, v140
	v_cmp_ge_i32_e64 s[14:15], v68, v138
	v_add_f32_e32 v69, 1.0, v69
	s_and_b64 s[14:15], vcc, s[14:15]
	v_log_f32_e32 v69, v69
	v_cndmask_b32_e64 v68, -v67, 0, s[14:15]
	v_sub_f32_e32 v67, v71, v67
	v_cndmask_b32_e64 v149, v67, v238, s[14:15]
	v_max_f32_e32 v67, 0, v72
	v_add_f32_e32 v67, v67, v69
	v_subrev_u32_e32 v69, 53, v140
	v_cmp_ge_i32_e64 s[14:15], v69, v138
	v_exp_f32_e64 v69, -|v73|
	s_and_b64 s[14:15], vcc, s[14:15]
	v_cndmask_b32_e64 v82, -v67, 0, s[14:15]
	v_sub_f32_e32 v67, v72, v67
	v_add_f32_e32 v69, 1.0, v69
	v_log_f32_e32 v69, v69
	v_cndmask_b32_e64 v72, v67, v238, s[14:15]
	v_max_f32_e32 v67, 0, v73
	v_add_f32_e32 v67, v67, v69
	v_subrev_u32_e32 v69, 52, v140
	v_cmp_ge_i32_e64 s[14:15], v69, v138
	v_exp_f32_e64 v69, -|v74|
	s_and_b64 s[14:15], vcc, s[14:15]
	v_cndmask_b32_e64 v70, -v67, 0, s[14:15]
	v_sub_f32_e32 v67, v73, v67
	v_add_f32_e32 v69, 1.0, v69
	v_log_f32_e32 v69, v69
	v_exp_f32_e64 v71, -|v75|
	v_cndmask_b32_e64 v73, v67, v238, s[14:15]
	v_max_f32_e32 v67, 0, v74
	v_add_f32_e32 v67, v67, v69
	v_subrev_u32_e32 v69, 47, v140
	v_cmp_ge_i32_e64 s[14:15], v69, v138
	v_add_f32_e32 v71, 1.0, v71
	s_and_b64 s[14:15], vcc, s[14:15]
	v_log_f32_e32 v71, v71
	v_cndmask_b32_e64 v69, -v67, 0, s[14:15]
	v_sub_f32_e32 v67, v74, v67
	v_cndmask_b32_e64 v150, v67, v238, s[14:15]
	v_max_f32_e32 v67, 0, v75
	v_add_f32_e32 v67, v67, v71
	v_subrev_u32_e32 v71, 46, v140
	v_cmp_ge_i32_e64 s[14:15], v71, v138
	v_exp_f32_e64 v71, -|v76|
	s_and_b64 s[14:15], vcc, s[14:15]
	v_cndmask_b32_e64 v151, -v67, 0, s[14:15]
	v_sub_f32_e32 v67, v75, v67
	v_add_f32_e32 v71, 1.0, v71
	v_log_f32_e32 v71, v71
	v_cndmask_b32_e64 v152, v67, v238, s[14:15]
	v_max_f32_e32 v67, 0, v76
	v_add_f32_e32 v67, v67, v71
	v_subrev_u32_e32 v71, 45, v140
	v_cmp_ge_i32_e64 s[14:15], v71, v138
	v_exp_f32_e64 v71, -|v77|
	s_and_b64 s[14:15], vcc, s[14:15]
	v_cndmask_b32_e64 v153, -v67, 0, s[14:15]
	v_sub_f32_e32 v67, v76, v67
	v_add_f32_e32 v71, 1.0, v71
	v_log_f32_e32 v71, v71
	v_cndmask_b32_e64 v76, v67, v238, s[14:15]
	v_max_f32_e32 v67, 0, v77
	v_add_f32_e32 v67, v67, v71
	v_subrev_u32_e32 v71, 44, v140
	v_cmp_ge_i32_e64 s[14:15], v71, v138
	v_exp_f32_e64 v71, -|v78|
	s_and_b64 s[14:15], vcc, s[14:15]
	v_cndmask_b32_e64 v154, -v67, 0, s[14:15]
	v_sub_f32_e32 v67, v77, v67
	v_add_f32_e32 v71, 1.0, v71
	v_log_f32_e32 v71, v71
	v_exp_f32_e64 v75, -|v79|
	v_cndmask_b32_e64 v77, v67, v238, s[14:15]
	v_max_f32_e32 v67, 0, v78
	v_add_f32_e32 v67, v67, v71
	v_subrev_u32_e32 v71, 39, v140
	v_cmp_ge_i32_e64 s[14:15], v71, v138
	v_add_f32_e32 v75, 1.0, v75
	s_and_b64 s[14:15], vcc, s[14:15]
	v_log_f32_e32 v75, v75
	v_cndmask_b32_e64 v71, -v67, 0, s[14:15]
	v_sub_f32_e32 v67, v78, v67
	v_cndmask_b32_e64 v74, v67, v238, s[14:15]
	v_max_f32_e32 v67, 0, v79
	v_add_f32_e32 v67, v67, v75
	v_subrev_u32_e32 v75, 38, v140
	v_cmp_ge_i32_e64 s[14:15], v75, v138
	s_and_b64 s[14:15], vcc, s[14:15]
	v_add_f32_e32 v155, 1.0, v155
	v_cndmask_b32_e64 v75, -v67, 0, s[14:15]
	v_sub_f32_e32 v67, v79, v67
	v_exp_f32_e64 v79, -|v80|
	v_cndmask_b32_e64 v78, v67, v238, s[14:15]
	v_max_f32_e32 v67, 0, v80
	v_add_f32_e32 v79, 1.0, v79
	v_log_f32_e32 v79, v79
	v_log_f32_e32 v155, v155
	v_add_f32_e32 v71, v71, v75
	v_exp_f32_e32 v85, v85
	v_add_f32_e32 v67, v67, v79
	v_subrev_u32_e32 v79, 37, v140
	v_cmp_ge_i32_e64 s[14:15], v79, v138
	s_and_b64 s[14:15], vcc, s[14:15]
	v_exp_f32_e32 v95, v95
	v_cndmask_b32_e64 v79, -v67, 0, s[14:15]
	v_sub_f32_e32 v67, v80, v67
	v_cndmask_b32_e64 v80, v67, v238, s[14:15]
	v_max_f32_e32 v67, 0, v81
	v_add_f32_e32 v67, v67, v155
	v_subrev_u32_e32 v155, 36, v140
	v_cmp_ge_i32_e64 s[14:15], v155, v138
	s_and_b64 vcc, vcc, s[14:15]
	v_cndmask_b32_e64 v155, -v67, 0, vcc
	v_add_f32_e32 v159, v79, v155
	v_add_f32_e32 v71, v71, v159
	ds_bpermute_b32 v159, v86, v71
	v_sub_f32_e32 v67, v81, v67
	v_cndmask_b32_e32 v81, v67, v238, vcc
	v_add_f32_e32 v67, v145, v141
	v_add_f32_e32 v145, v143, v146
	v_add_f32_e32 v145, v67, v145
	v_add_f32_e32 v67, v69, v151
	v_add_f32_e32 v69, v153, v154
	v_add_f32_e32 v67, v67, v69
	s_waitcnt lgkmcnt(0)
	v_cndmask_b32_e64 v160, 0, v159, s[12:13]
	ds_bpermute_b32 v69, v86, v67
	v_add_f32_e32 v160, v83, v160
	v_add_f32_e32 v155, v155, v160
	v_add_f32_e32 v79, v79, v155
	v_add_f32_e32 v75, v75, v79
	v_add_f32_e32 v74, v74, v75
	v_add_f32_e32 v71, v71, v159
	v_add_f32_e32 v81, v81, v160
	v_exp_f32_e32 v160, v74
	v_pk_add_f32 v[74:75], v[82:83], v[70:71]
	s_waitcnt lgkmcnt(0)
	v_pk_add_f32 v[66:67], v[66:67], v[68:69]
	v_add_f32_e32 v78, v78, v79
	v_pk_add_f32 v[66:67], v[66:67], v[74:75]
	v_add_f32_e32 v80, v80, v155
	v_exp_f32_e32 v155, v78
	v_cndmask_b32_e64 v78, 0, v69, s[12:13]
	ds_bpermute_b32 v69, v86, v66
	ds_bpermute_b32 v158, v86, v145
	v_add_f32_e32 v71, v78, v75
	v_add_f32_e32 v74, v77, v71
	v_add_f32_e32 v71, v154, v71
	v_exp_f32_e32 v83, v74
	v_add_f32_e32 v74, v76, v71
	v_add_f32_e32 v71, v153, v71
	v_exp_f32_e32 v154, v74
	v_add_f32_e32 v74, v152, v71
	v_exp_f32_e32 v152, v74
	s_waitcnt lgkmcnt(1)
; #define LAS __attribute__((address_space(3)))
; #define MFMA32(a, b, c) __builtin_amdgcn_mfma_f32_32x32x16_bf16((a), (b), (c), 0, 0, 0)
; __device__ __forceinline__ float fexp2(float x) { return __builtin_amdgcn_exp2f(x); }
; __device__ __forceinline__ float flog2(float x) { return __builtin_amdgcn_logf(x); }
; __device__ __forceinline__ void stick_block(f32x16& s, float& Rr, int t, int kbase, int h, bool diag) {
;     float u[16], gs[4], pg[4];
; #pragma unroll
;     for (int i = 0; i < 16; ++i) {
;         const float z = s[i];
;         const float sp = fmaxf(z, 0.f) + flog2(1.0f + fexp2(-fabsf(z)));
;         const int j = kbase + (i & 3) + 8 * (i >> 2) + 4 * h;
;         const bool valid = !diag || (j < t);
;         u[i] = valid ? -sp : 0.f;
;         s[i] = valid ? (z - sp) : -__builtin_inff();
; __device__ __forceinline__ void pv_tile(LAS unsigned char* vt, const f32x16& s0, const f32x16& s1, int h, int lane, f32x16 (&o)[2]) {
; #pragma unroll
;     for (int st = 0; st < 2; ++st) {
;         const bf16x8 pb = pack8(s0, st);
; #pragma unroll
;         for (int db = 0; db < 2; ++db) o[db] = MFMA32(vfrag<64>(vt, 32 * db, 16 * st + 4 * h, lane), pb, o[db]);
;     }
; #pragma unroll
;     for (int st = 0; st < 2; ++st) {
;         const bf16x8 pb = pack8(s1, st);
; #pragma unroll
;         for (int db = 0; db < 2; ++db) o[db] = MFMA32(vfrag<64>(vt, 32 * db, 32 + 16 * st + 4 * h, lane), pb, o[db]);
;     }
	v_cndmask_b32_e64 v74, 0, v69, s[12:13]
	v_add_f32_e32 v66, v66, v69
	v_add_f32_e32 v74, v74, v67
	v_add_f32_e32 v67, v66, v67
	s_waitcnt lgkmcnt(0)
	v_cndmask_b32_e64 v66, 0, v158, s[12:13]
	v_add_f32_e32 v70, v70, v74
	v_add_f32_e32 v66, v66, v67
	v_add_f32_e32 v72, v72, v70
	v_add_f32_e32 v70, v82, v70
	v_add_f32_e32 v69, v147, v66
	v_add_f32_e32 v66, v146, v66
	v_add_f32_e32 v73, v73, v74
	v_exp_f32_e32 v76, v72
	v_add_f32_e32 v72, v149, v70
	v_add_f32_e32 v68, v68, v70
	v_exp_f32_e32 v70, v69
	v_add_f32_e32 v69, v144, v66
	v_exp_f32_e32 v75, v73
	v_exp_f32_e32 v73, v69
	v_add_f32_e32 v66, v143, v66
	v_add_f32_e32 v69, v142, v66
	v_add_f32_e32 v66, v141, v66
	v_add_f32_e32 v68, v148, v68
	v_add_f32_e32 v66, v135, v66
	v_cvt_pk_bf16_f32 v73, v73, v70
	v_add_u32_e32 v70, s45, v200
	v_exp_f32_e32 v74, v72
	v_exp_f32_e32 v68, v68
	v_exp_f32_e32 v72, v69
	v_exp_f32_e32 v66, v66
	v_cvt_pk_bf16_f32 v75, v76, v75
	ds_read_b64_tr_b16 v[76:77], v70 offset:36864
	ds_read_b64_tr_b16 v[78:79], v70 offset:38016
	v_cvt_pk_bf16_f32 v74, v68, v74
	v_cvt_pk_bf16_f32 v72, v66, v72
	v_add_f32_e32 v71, v151, v71
	v_add_f32_e32 v71, v150, v71
	s_waitcnt lgkmcnt(0)
	v_mfma_f32_32x32x16_bf16 v[18:33], v[76:79], v[72:75], v[18:33]
	ds_read_b64_tr_b16 v[76:77], v70 offset:36928
	ds_read_b64_tr_b16 v[78:79], v70 offset:38080
	v_exp_f32_e32 v81, v81
	v_exp_f32_e32 v80, v80
	v_exp_f32_e32 v71, v71
	v_exp_f32_e32 v96, v96
	v_exp_f32_e32 v97, v97
	v_exp_f32_e32 v133, v133
	s_waitcnt lgkmcnt(0)
	v_mfma_f32_32x32x16_bf16 v[2:17], v[76:79], v[72:75], v[2:17]
	ds_read_b64_tr_b16 v[76:77], v70 offset:39168
	ds_read_b64_tr_b16 v[78:79], v70 offset:40320
	v_cvt_pk_bf16_f32 v72, v71, v152
	v_cvt_pk_bf16_f32 v73, v154, v83
	v_cvt_pk_bf16_f32 v74, v160, v155
	v_cvt_pk_bf16_f32 v75, v80, v81
	v_exp_f32_e32 v84, v84
	v_exp_f32_e32 v132, v132
	s_waitcnt lgkmcnt(0)
	v_mfma_f32_32x32x16_bf16 v[18:33], v[76:79], v[72:75], v[18:33]
	ds_read_b64_tr_b16 v[76:77], v70 offset:39232
	ds_read_b64_tr_b16 v[78:79], v70 offset:40384
	v_exp_f32_e64 v71, -|v50|
	v_add_u32_e32 v66, 0xffffffa1, v140
	v_exp_f32_e32 v87, v87
	v_exp_f32_e32 v88, v88
	v_exp_f32_e32 v89, v89
	v_exp_f32_e32 v91, v91
	s_waitcnt lgkmcnt(0)
	v_mfma_f32_32x32x16_bf16 v[2:17], v[76:79], v[72:75], v[2:17]
	ds_read_b64_tr_b16 v[76:77], v70 offset:41472
	ds_read_b64_tr_b16 v[78:79], v70 offset:42624
	v_cvt_pk_bf16_f32 v72, v134, v132
	v_cvt_pk_bf16_f32 v73, v84, v133
	v_cvt_pk_bf16_f32 v74, v97, v96
	v_cvt_pk_bf16_f32 v75, v95, v85
	v_exp_f32_e32 v92, v92
	v_exp_f32_e32 v93, v93
	s_waitcnt lgkmcnt(0)
	v_mfma_f32_32x32x16_bf16 v[18:33], v[76:79], v[72:75], v[18:33]
	ds_read_b64_tr_b16 v[76:77], v70 offset:41536
	ds_read_b64_tr_b16 v[78:79], v70 offset:42688
	v_exp_f32_e32 v94, v94
	v_add_f32_e32 v71, 1.0, v71
	v_cmp_ge_i32_e64 s[14:15], v66, v138
	v_exp_f32_e64 v66, -|v51|
	v_log_f32_e32 v71, v71
	s_waitcnt lgkmcnt(0)
	v_mfma_f32_32x32x16_bf16 v[2:17], v[76:79], v[72:75], v[2:17]
	ds_read_b64_tr_b16 v[76:77], v70 offset:43776
	ds_read_b64_tr_b16 v[78:79], v70 offset:44928
	v_cvt_pk_bf16_f32 v72, v94, v93
	v_cvt_pk_bf16_f32 v73, v92, v91
	v_cvt_pk_bf16_f32 v74, v90, v89
	v_cvt_pk_bf16_f32 v75, v88, v87
	v_max_f32_e32 v68, 0, v50
	v_add_f32_e32 v66, 1.0, v66
	s_waitcnt lgkmcnt(0)
	v_mfma_f32_32x32x16_bf16 v[18:33], v[76:79], v[72:75], v[18:33]
	ds_read_b64_tr_b16 v[76:77], v70 offset:43840
	ds_read_b64_tr_b16 v[78:79], v70 offset:44992
	v_cmp_gt_i32_e32 vcc, s44, v137
	v_add_f32_e32 v68, v68, v71
	v_log_f32_e32 v66, v66
	s_and_b64 s[14:15], vcc, s[14:15]
	v_sub_f32_e32 v50, v50, v68
	v_cndmask_b32_e64 v71, v50, v238, s[14:15]
	v_max_f32_e32 v50, 0, v51
	v_add_f32_e32 v50, v50, v66
	v_add_u32_e32 v66, 0xffffffa2, v140
	s_waitcnt lgkmcnt(0)
	v_mfma_f32_32x32x16_bf16 v[2:17], v[76:79], v[72:75], v[2:17]
	v_cndmask_b32_e64 v78, -v68, 0, s[14:15]
	v_cmp_ge_i32_e64 s[14:15], v66, v138
	s_and_b64 s[14:15], vcc, s[14:15]
	v_add_f32_e32 v69, v145, v158
	v_cndmask_b32_e64 v72, -v50, 0, s[14:15]
	v_sub_f32_e32 v50, v51, v50
	v_exp_f32_e64 v51, -|v52|
	v_cndmask_b32_e64 v73, v50, v238, s[14:15]
	v_max_f32_e32 v50, 0, v52
	v_add_f32_e32 v51, 1.0, v51
	v_log_f32_e32 v51, v51
	v_add_u32_e32 v82, 0xffffff81, v140
	v_add_f32_e32 v50, v50, v51
	v_add_u32_e32 v51, 0xffffffa3, v140
	v_cmp_ge_i32_e64 s[14:15], v51, v138
	v_exp_f32_e64 v51, -|v53|
	s_and_b64 s[14:15], vcc, s[14:15]
	v_cndmask_b32_e64 v74, -v50, 0, s[14:15]
	v_sub_f32_e32 v50, v52, v50
	v_add_f32_e32 v51, 1.0, v51
	v_log_f32_e32 v51, v51
	v_cndmask_b32_e64 v75, v50, v238, s[14:15]
	v_max_f32_e32 v50, 0, v53
	v_add_f32_e32 v50, v50, v51
	v_add_u32_e32 v51, 0xffffffa4, v140
	v_cmp_ge_i32_e64 s[14:15], v51, v138
	v_exp_f32_e64 v51, -|v54|
	s_and_b64 s[14:15], vcc, s[14:15]
	v_cndmask_b32_e64 v76, -v50, 0, s[14:15]
	v_sub_f32_e32 v50, v53, v50
	v_add_f32_e32 v51, 1.0, v51
	v_log_f32_e32 v51, v51
	v_exp_f32_e64 v52, -|v55|
	v_cndmask_b32_e64 v77, v50, v238, s[14:15]
	v_max_f32_e32 v50, 0, v54
	v_add_f32_e32 v50, v50, v51
	v_add_u32_e32 v51, 0xffffffa9, v140
	v_cmp_ge_i32_e64 s[14:15], v51, v138
	v_add_f32_e32 v52, 1.0, v52
	s_and_b64 s[14:15], vcc, s[14:15]
	v_log_f32_e32 v52, v52
	v_cndmask_b32_e64 v79, -v50, 0, s[14:15]
	v_sub_f32_e32 v50, v54, v50
	v_cndmask_b32_e64 v51, v50, v238, s[14:15]
	v_max_f32_e32 v50, 0, v55
	v_add_f32_e32 v50, v50, v52
	v_add_u32_e32 v52, 0xffffffaa, v140
	v_cmp_ge_i32_e64 s[14:15], v52, v138
	v_exp_f32_e64 v52, -|v56|
	s_and_b64 s[14:15], vcc, s[14:15]
	v_cndmask_b32_e64 v53, -v50, 0, s[14:15]
	v_sub_f32_e32 v50, v55, v50
	v_add_f32_e32 v52, 1.0, v52
	v_log_f32_e32 v52, v52
	v_cndmask_b32_e64 v80, v50, v238, s[14:15]
	v_max_f32_e32 v50, 0, v56
; __device__ __forceinline__ float fexp2(float x) { return __builtin_amdgcn_exp2f(x); }
; __device__ __forceinline__ float flog2(float x) { return __builtin_amdgcn_logf(x); }
; __device__ __forceinline__ void stick_block(f32x16& s, float& Rr, int t, int kbase, int h, bool diag) {
;     float u[16], gs[4], pg[4];
; #pragma unroll
;     for (int i = 0; i < 16; ++i) {
;         const float z = s[i];
;         const float sp = fmaxf(z, 0.f) + flog2(1.0f + fexp2(-fabsf(z)));
;         const int j = kbase + (i & 3) + 8 * (i >> 2) + 4 * h;
;         const bool valid = !diag || (j < t);
;         u[i] = valid ? -sp : 0.f;
;         s[i] = valid ? (z - sp) : -__builtin_inff();
;     }
; #pragma unroll
;     for (int c = 0; c < 4; ++c) { gs[c] = (u[4 * c] + u[4 * c + 1]) + (u[4 * c + 2] + u[4 * c + 3]); pg[c] = __shfl_xor(gs[c], 32); }
;     float run = Rr;
; #pragma unroll
;     for (int c = 3; c >= 0; --c) {
;         float tl = run + ((h == 0) ? pg[c] : 0.f);
; #pragma unroll
;     ...
;         run += gs[c] + pg[c];
;     }
;     Rr = run;
	v_add_f32_e32 v50, v50, v52
	v_add_u32_e32 v52, 0xffffffab, v140
	v_cmp_ge_i32_e64 s[14:15], v52, v138
	v_exp_f32_e64 v52, -|v57|
	s_and_b64 s[14:15], vcc, s[14:15]
	v_cndmask_b32_e64 v81, -v50, 0, s[14:15]
	v_sub_f32_e32 v50, v56, v50
	v_add_f32_e32 v52, 1.0, v52
	v_log_f32_e32 v52, v52
	v_cndmask_b32_e64 v83, v50, v238, s[14:15]
	v_max_f32_e32 v50, 0, v57
	v_add_f32_e32 v50, v50, v52
	v_add_u32_e32 v52, 0xffffffac, v140
	v_cmp_ge_i32_e64 s[14:15], v52, v138
	v_exp_f32_e64 v52, -|v58|
	s_and_b64 s[14:15], vcc, s[14:15]
	v_cndmask_b32_e64 v84, -v50, 0, s[14:15]
	v_sub_f32_e32 v50, v57, v50
	v_add_f32_e32 v52, 1.0, v52
	v_log_f32_e32 v52, v52
	v_cndmask_b32_e64 v85, v50, v238, s[14:15]
	v_max_f32_e32 v50, 0, v58
	v_add_f32_e32 v50, v50, v52
	v_add_u32_e32 v52, 0xffffffb1, v140
	v_cmp_ge_i32_e64 s[14:15], v52, v138
	v_exp_f32_e64 v52, -|v59|
	s_and_b64 s[14:15], vcc, s[14:15]
	v_cndmask_b32_e64 v68, -v50, 0, s[14:15]
	v_sub_f32_e32 v50, v58, v50
	v_add_f32_e32 v52, 1.0, v52
	v_log_f32_e32 v52, v52
	v_cndmask_b32_e64 v87, v50, v238, s[14:15]
	v_max_f32_e32 v50, 0, v59
	v_add_f32_e32 v50, v50, v52
	v_add_u32_e32 v52, 0xffffffb2, v140
	v_cmp_ge_i32_e64 s[14:15], v52, v138
	v_exp_f32_e64 v52, -|v60|
	s_and_b64 s[14:15], vcc, s[14:15]
	v_cndmask_b32_e64 v66, -v50, 0, s[14:15]
	v_sub_f32_e32 v50, v59, v50
	v_add_f32_e32 v52, 1.0, v52
	v_log_f32_e32 v52, v52
	v_cndmask_b32_e64 v88, v50, v238, s[14:15]
	v_max_f32_e32 v50, 0, v60
	v_add_f32_e32 v50, v50, v52
	v_add_u32_e32 v52, 0xffffffb3, v140
	v_cmp_ge_i32_e64 s[14:15], v52, v138
	v_exp_f32_e64 v52, -|v61|
	s_and_b64 s[14:15], vcc, s[14:15]
	v_cndmask_b32_e64 v54, -v50, 0, s[14:15]
	v_sub_f32_e32 v50, v60, v50
	v_add_f32_e32 v52, 1.0, v52
	v_log_f32_e32 v52, v52
	v_cndmask_b32_e64 v89, v50, v238, s[14:15]
	v_max_f32_e32 v50, 0, v61
	v_add_f32_e32 v50, v50, v52
	v_add_u32_e32 v52, 0xffffffb4, v140
	v_cmp_ge_i32_e64 s[14:15], v52, v138
	v_exp_f32_e64 v52, -|v62|
	s_and_b64 s[14:15], vcc, s[14:15]
	v_cndmask_b32_e64 v56, -v50, 0, s[14:15]
	v_sub_f32_e32 v50, v61, v50
	v_add_f32_e32 v52, 1.0, v52
	v_log_f32_e32 v52, v52
	v_cndmask_b32_e64 v90, v50, v238, s[14:15]
	v_max_f32_e32 v50, 0, v62
	v_add_f32_e32 v50, v50, v52
	v_add_u32_e32 v52, 0xffffffb9, v140
	v_cmp_ge_i32_e64 s[14:15], v52, v138
	v_exp_f32_e64 v52, -|v63|
	s_and_b64 s[14:15], vcc, s[14:15]
	v_cndmask_b32_e64 v55, -v50, 0, s[14:15]
	v_sub_f32_e32 v50, v62, v50
	v_add_f32_e32 v52, 1.0, v52
	v_log_f32_e32 v52, v52
	v_cndmask_b32_e64 v91, v50, v238, s[14:15]
	v_max_f32_e32 v50, 0, v63
	v_add_f32_e32 v50, v50, v52
	v_add_u32_e32 v52, 0xffffffba, v140
	v_cmp_ge_i32_e64 s[14:15], v52, v138
	v_exp_f32_e64 v52, -|v64|
	s_and_b64 s[14:15], vcc, s[14:15]
	v_cndmask_b32_e64 v92, -v50, 0, s[14:15]
	v_sub_f32_e32 v50, v63, v50
	v_add_f32_e32 v52, 1.0, v52
	v_log_f32_e32 v52, v52
	v_cndmask_b32_e64 v93, v50, v238, s[14:15]
	v_max_f32_e32 v50, 0, v64
	v_add_f32_e32 v50, v50, v52
	v_add_u32_e32 v52, 0xffffffbb, v140
	v_cmp_ge_i32_e64 s[14:15], v52, v138
	v_exp_f32_e64 v52, -|v65|
	s_and_b64 s[14:15], vcc, s[14:15]
	v_cndmask_b32_e64 v94, -v50, 0, s[14:15]
	v_sub_f32_e32 v50, v64, v50
	v_add_f32_e32 v52, 1.0, v52
	v_log_f32_e32 v52, v52
	v_cndmask_b32_e64 v63, v50, v238, s[14:15]
	v_max_f32_e32 v50, 0, v65
	v_add_f32_e32 v50, v50, v52
	v_add_u32_e32 v52, 0xffffffbc, v140
	v_cmp_ge_i32_e64 s[14:15], v52, v138
	s_and_b64 s[14:15], vcc, s[14:15]
	v_add_f32_e32 v57, v79, v53
	v_cndmask_b32_e64 v64, -v50, 0, s[14:15]
	v_add_f32_e32 v58, v81, v84
	v_add_f32_e32 v95, v57, v58
	v_add_f32_e32 v55, v55, v92
	v_add_f32_e32 v57, v94, v64
	v_add_f32_e32 v55, v55, v57
	ds_bpermute_b32 v57, v86, v55
	v_pk_add_f32 v[58:59], v[68:69], v[66:67]
	v_sub_f32_e32 v50, v65, v50
	v_cndmask_b32_e64 v62, v50, v238, s[14:15]
	ds_bpermute_b32 v96, v86, v95
	s_waitcnt lgkmcnt(1)
	v_pk_add_f32 v[60:61], v[54:55], v[56:57]
	v_cndmask_b32_e64 v65, 0, v57, s[12:13]
	v_pk_add_f32 v[60:61], v[58:59], v[60:61]
	ds_bpermute_b32 v55, v86, v60
	v_add_f32_e32 v57, v59, v65
	v_add_f32_e32 v58, v62, v57
	v_add_f32_e32 v57, v64, v57
	v_exp_f32_e32 v62, v58
	v_add_f32_e32 v58, v63, v57
	v_add_f32_e32 v57, v94, v57
	v_exp_f32_e32 v63, v58
	v_add_f32_e32 v58, v93, v57
	v_add_f32_e32 v57, v92, v57
	v_add_f32_e32 v57, v91, v57
	v_exp_f32_e32 v65, v57
	s_waitcnt lgkmcnt(0)
	v_cndmask_b32_e64 v57, 0, v55, s[12:13]
	v_add_f32_e32 v57, v57, v61
	v_add_f32_e32 v56, v56, v57
	v_add_f32_e32 v54, v54, v56
	v_exp_f32_e32 v64, v58
	v_add_f32_e32 v58, v90, v57
	v_add_f32_e32 v57, v89, v56
	v_add_f32_e32 v56, v88, v54
	v_add_f32_e32 v54, v66, v54
	v_add_f32_e32 v54, v87, v54
	v_exp_f32_e32 v66, v54
	v_add_f32_e32 v54, v60, v55
	v_add_f32_e32 v54, v54, v61
	v_cndmask_b32_e64 v55, 0, v96, s[12:13]
	v_add_f32_e32 v55, v55, v54
	v_exp_f32_e32 v69, v56
	v_add_f32_e32 v56, v85, v55
	v_add_f32_e32 v55, v84, v55
	v_add_f32_e32 v50, v78, v72
	v_exp_f32_e32 v78, v56
	v_add_f32_e32 v56, v83, v55
	v_add_f32_e32 v55, v81, v55
	v_add_f32_e32 v53, v53, v55
	v_add_f32_e32 v51, v51, v53
	v_exp_f32_e64 v53, -|v34|
	v_exp_f32_e32 v81, v51
	v_max_f32_e32 v51, 0, v34
	v_add_f32_e32 v53, 1.0, v53
	v_log_f32_e32 v53, v53
	v_cmp_ge_i32_e64 s[14:15], v82, v138
	s_and_b64 s[14:15], vcc, s[14:15]
	v_exp_f32_e32 v67, v58
	v_add_f32_e32 v51, v51, v53
	v_cndmask_b32_e64 v58, -v51, 0, s[14:15]
	v_sub_f32_e32 v34, v34, v51
	v_exp_f32_e64 v51, -|v35|
	v_cndmask_b32_e64 v82, v34, v238, s[14:15]
	v_max_f32_e32 v34, 0, v35
	v_add_f32_e32 v51, 1.0, v51
	v_log_f32_e32 v51, v51
	v_exp_f32_e32 v79, v56
	v_add_f32_e32 v56, v80, v55
	v_exp_f32_e32 v80, v56
	v_add_f32_e32 v51, v34, v51
	v_add_u32_e32 v34, 0xffffff82, v140
	v_cmp_ge_i32_e64 s[14:15], v34, v138
	s_and_b64 s[14:15], vcc, s[14:15]
	v_sub_f32_e32 v35, v35, v51
	v_cndmask_b32_e64 v34, -v51, 0, s[14:15]
	v_exp_f32_e64 v51, -|v36|
	v_cndmask_b32_e64 v83, v35, v238, s[14:15]
	v_max_f32_e32 v35, 0, v36
	v_add_f32_e32 v51, 1.0, v51
	v_log_f32_e32 v51, v51
	v_add_f32_e32 v56, v95, v96
	v_exp_f32_e32 v68, v57
	v_add_f32_e32 v52, v74, v76
	v_add_f32_e32 v35, v35, v51
	v_add_u32_e32 v51, 0xffffff83, v140
	v_cmp_ge_i32_e64 s[14:15], v51, v138
	s_and_b64 s[14:15], vcc, s[14:15]
	v_exp_f32_e64 v51, -|v39|
	v_cndmask_b32_e64 v60, -v35, 0, s[14:15]
	v_sub_f32_e32 v35, v36, v35
	v_exp_f32_e64 v36, -|v37|
	v_cndmask_b32_e64 v84, v35, v238, s[14:15]
	v_max_f32_e32 v35, 0, v37
	v_add_f32_e32 v36, 1.0, v36
	v_log_f32_e32 v36, v36
	v_add_f32_e32 v51, 1.0, v51
	v_log_f32_e32 v51, v51
	v_add_f32_e32 v52, v50, v52
	v_add_f32_e32 v35, v35, v36
	v_add_u32_e32 v36, 0xffffff84, v140
	v_cmp_ge_i32_e64 s[14:15], v36, v138
	s_and_b64 s[14:15], vcc, s[14:15]
	ds_bpermute_b32 v50, v86, v52
	v_cndmask_b32_e64 v36, -v35, 0, s[14:15]
	v_sub_f32_e32 v35, v37, v35
	v_exp_f32_e64 v37, -|v38|
	v_cndmask_b32_e64 v85, v35, v238, s[14:15]
	v_max_f32_e32 v35, 0, v38
	v_add_f32_e32 v37, 1.0, v37
	v_log_f32_e32 v37, v37
	s_waitcnt lgkmcnt(0)
; __device__ __forceinline__ float fexp2(float x) { return __builtin_amdgcn_exp2f(x); }
; __device__ __forceinline__ float flog2(float x) { return __builtin_amdgcn_logf(x); }
; __device__ __forceinline__ void stick_block(f32x16& s, float& Rr, int t, int kbase, int h, bool diag) {
;     float u[16], gs[4], pg[4];
; #pragma unroll
;     for (int i = 0; i < 16; ++i) {
;         const float z = s[i];
;         const float sp = fmaxf(z, 0.f) + flog2(1.0f + fexp2(-fabsf(z)));
;         const int j = kbase + (i & 3) + 8 * (i >> 2) + 4 * h;
;         const bool valid = !diag || (j < t);
;         u[i] = valid ? -sp : 0.f;
;         s[i] = valid ? (z - sp) : -__builtin_inff();
;     }
; #pragma unroll
;     for (int c = 0; c < 4; ++c) { gs[c] = (u[4 * c] + u[4 * c + 1]) + (u[4 * c + 2] + u[4 * c + 3]); pg[c] = __shfl_xor(gs[c], 32); }
	v_cndmask_b32_e64 v61, 0, v50, s[12:13]
	v_add_f32_e32 v37, v35, v37
	v_add_u32_e32 v35, 0xffffff89, v140
	v_cmp_ge_i32_e64 s[14:15], v35, v138
	s_and_b64 s[14:15], vcc, s[14:15]
	s_nop 0
	v_cndmask_b32_e64 v35, -v37, 0, s[14:15]
	v_sub_f32_e32 v37, v38, v37
	v_cndmask_b32_e64 v38, v37, v238, s[14:15]
	v_max_f32_e32 v37, 0, v39
	v_add_f32_e32 v37, v37, v51
	v_add_u32_e32 v51, 0xffffff8a, v140
	v_cmp_ge_i32_e64 s[14:15], v51, v138
	v_exp_f32_e64 v51, -|v40|
	s_and_b64 s[14:15], vcc, s[14:15]
	v_cndmask_b32_e64 v87, -v37, 0, s[14:15]
	v_sub_f32_e32 v37, v39, v37
	v_add_f32_e32 v51, 1.0, v51
	v_log_f32_e32 v51, v51
	v_cndmask_b32_e64 v39, v37, v238, s[14:15]
	v_max_f32_e32 v37, 0, v40
	v_add_f32_e32 v37, v37, v51
	v_add_u32_e32 v51, 0xffffff8b, v140
	v_cmp_ge_i32_e64 s[14:15], v51, v138
	v_exp_f32_e64 v51, -|v41|
	s_and_b64 s[14:15], vcc, s[14:15]
	v_cndmask_b32_e64 v88, -v37, 0, s[14:15]
	v_sub_f32_e32 v37, v40, v37
	v_add_f32_e32 v51, 1.0, v51
	v_log_f32_e32 v51, v51
	v_cndmask_b32_e64 v40, v37, v238, s[14:15]
	v_max_f32_e32 v37, 0, v41
	v_add_f32_e32 v37, v37, v51
	v_add_u32_e32 v51, 0xffffff8c, v140
	v_cmp_ge_i32_e64 s[14:15], v51, v138
	v_exp_f32_e64 v51, -|v42|
	s_and_b64 s[14:15], vcc, s[14:15]
	v_cndmask_b32_e64 v89, -v37, 0, s[14:15]
	v_sub_f32_e32 v37, v41, v37
	v_add_f32_e32 v51, 1.0, v51
	v_log_f32_e32 v51, v51
	v_cndmask_b32_e64 v41, v37, v238, s[14:15]
	v_max_f32_e32 v37, 0, v42
	v_add_f32_e32 v37, v37, v51
	v_add_u32_e32 v51, 0xffffff91, v140
	v_cmp_ge_i32_e64 s[14:15], v51, v138
	v_exp_f32_e64 v51, -|v43|
	s_and_b64 s[14:15], vcc, s[14:15]
	v_cndmask_b32_e64 v90, -v37, 0, s[14:15]
	v_sub_f32_e32 v37, v42, v37
	v_add_f32_e32 v51, 1.0, v51
	v_log_f32_e32 v51, v51
	v_cndmask_b32_e64 v42, v37, v238, s[14:15]
	v_max_f32_e32 v37, 0, v43
	v_add_f32_e32 v37, v37, v51
	v_add_u32_e32 v51, 0xffffff92, v140
	v_cmp_ge_i32_e64 s[14:15], v51, v138
	v_exp_f32_e64 v51, -|v44|
	s_and_b64 s[14:15], vcc, s[14:15]
	v_cndmask_b32_e64 v91, -v37, 0, s[14:15]
	v_sub_f32_e32 v37, v43, v37
	v_add_f32_e32 v51, 1.0, v51
	v_log_f32_e32 v51, v51
	v_cndmask_b32_e64 v43, v37, v238, s[14:15]
	v_max_f32_e32 v37, 0, v44
	v_add_f32_e32 v37, v37, v51
	v_add_u32_e32 v51, 0xffffff93, v140
	v_cmp_ge_i32_e64 s[14:15], v51, v138
	s_and_b64 s[14:15], vcc, s[14:15]
	v_add_f32_e32 v35, v35, v87
	v_cndmask_b32_e64 v92, -v37, 0, s[14:15]
	v_sub_f32_e32 v37, v44, v37
	v_exp_f32_e64 v44, -|v45|
	v_cndmask_b32_e64 v93, v37, v238, s[14:15]
	v_max_f32_e32 v37, 0, v45
	v_add_f32_e32 v44, 1.0, v44
	v_log_f32_e32 v44, v44
	s_nop 0
	v_add_f32_e32 v37, v37, v44
	v_add_u32_e32 v44, 0xffffff94, v140
	v_cmp_ge_i32_e64 s[14:15], v44, v138
	v_exp_f32_e64 v44, -|v46|
	s_and_b64 s[14:15], vcc, s[14:15]
	v_cndmask_b32_e64 v94, -v37, 0, s[14:15]
	v_sub_f32_e32 v37, v45, v37
	v_exp_f32_e64 v45, -|v47|
	v_add_f32_e32 v44, 1.0, v44
	v_log_f32_e32 v44, v44
	v_cndmask_b32_e64 v95, v37, v238, s[14:15]
	v_add_f32_e32 v45, 1.0, v45
	v_max_f32_e32 v37, 0, v46
	v_log_f32_e32 v45, v45
	v_add_f32_e32 v37, v37, v44
	v_add_u32_e32 v44, 0xffffff99, v140
	v_cmp_ge_i32_e64 s[14:15], v44, v138
	s_and_b64 s[14:15], vcc, s[14:15]
	v_max_f32_e32 v44, 0, v47
	v_cndmask_b32_e64 v53, -v37, 0, s[14:15]
	v_sub_f32_e32 v37, v46, v37
	v_add_f32_e32 v44, v44, v45
	v_add_u32_e32 v45, 0xffffff9a, v140
	v_cndmask_b32_e64 v37, v37, v238, s[14:15]
	v_cmp_ge_i32_e64 s[14:15], v45, v138
	v_exp_f32_e64 v45, -|v48|
	s_and_b64 s[14:15], vcc, s[14:15]
	v_cndmask_b32_e64 v51, -v44, 0, s[14:15]
	v_sub_f32_e32 v44, v47, v44
	v_add_f32_e32 v45, 1.0, v45
	v_log_f32_e32 v45, v45
	v_cndmask_b32_e64 v96, v44, v238, s[14:15]
	v_max_f32_e32 v44, 0, v48
	v_add_f32_e32 v44, v44, v45
	v_add_u32_e32 v45, 0xffffff9b, v140
	v_cmp_ge_i32_e64 s[14:15], v45, v138
	v_exp_f32_e64 v45, -|v49|
	s_and_b64 s[14:15], vcc, s[14:15]
	v_cndmask_b32_e64 v57, -v44, 0, s[14:15]
	v_sub_f32_e32 v44, v48, v44
	v_add_f32_e32 v45, 1.0, v45
	v_log_f32_e32 v45, v45
	v_cndmask_b32_e64 v48, v44, v238, s[14:15]
	v_max_f32_e32 v44, 0, v49
	v_add_f32_e32 v44, v44, v45
	v_add_u32_e32 v45, 0xffffff9c, v140
	v_cmp_ge_i32_e64 s[14:15], v45, v138
	s_and_b64 vcc, vcc, s[14:15]
	v_cndmask_b32_e64 v55, -v44, 0, vcc
	v_sub_f32_e32 v44, v49, v44
	v_cndmask_b32_e32 v49, v44, v238, vcc
	v_add_f32_e32 v44, v88, v89
	v_add_f32_e32 v59, v35, v44
	v_add_f32_e32 v44, v90, v91
	v_add_f32_e32 v45, v92, v94
	v_add_f32_e32 v90, v44, v45
	v_pk_add_f32 v[44:45], v[56:57], v[54:55]
	ds_bpermute_b32 v97, v86, v90
	v_add_f32_e32 v46, v61, v44
	v_add_f32_e32 v47, v77, v46
	v_add_f32_e32 v46, v76, v46
	v_exp_f32_e32 v54, v47
	v_add_f32_e32 v47, v75, v46
	v_add_f32_e32 v46, v74, v46
	v_exp_f32_e32 v56, v47
	v_add_f32_e32 v47, v73, v46
	v_add_f32_e32 v46, v72, v46
	v_add_f32_e32 v46, v71, v46
	v_exp_f32_e32 v73, v47
	v_exp_f32_e32 v71, v46
	v_pk_add_f32 v[46:47], v[52:53], v[50:51]
	ds_bpermute_b32 v35, v86, v59
	v_pk_add_f32 v[44:45], v[46:47], v[44:45]
	ds_bpermute_b32 v46, v86, v45
	s_waitcnt lgkmcnt(2)
; #define LAS __attribute__((address_space(3)))
; #define MFMA32(a, b, c) __builtin_amdgcn_mfma_f32_32x32x16_bf16((a), (b), (c), 0, 0, 0)
; __device__ __forceinline__ void stick_block(f32x16& s, float& Rr, int t, int kbase, int h, bool diag) {
;     ...
;     for (int c = 0; c < 4; ++c) { gs[c] = (u[4 * c] + u[4 * c + 1]) + (u[4 * c + 2] + u[4 * c + 3]); pg[c] = __shfl_xor(gs[c], 32); }
;     float run = Rr;
; #pragma unroll
;     for (int c = 3; c >= 0; --c) {
;         float tl = run + ((h == 0) ? pg[c] : 0.f);
; #pragma unroll
;     ...
;         run += gs[c] + pg[c];
;     }
;     Rr = run;
; __device__ __forceinline__ void pv_tile(LAS unsigned char* vt, const f32x16& s0, const f32x16& s1, int h, int lane, f32x16 (&o)[2]) {
; #pragma unroll
;     for (int st = 0; st < 2; ++st) {
;         const bf16x8 pb = pack8(s0, st);
; #pragma unroll
;         for (int db = 0; db < 2; ++db) o[db] = MFMA32(vfrag<64>(vt, 32 * db, 16 * st + 4 * h, lane), pb, o[db]);
;     }
; #pragma unroll
;     for (int st = 0; st < 2; ++st) {
;         const bf16x8 pb = pack8(s1, st);
; #pragma unroll
;         for (int db = 0; db < 2; ++db) o[db] = MFMA32(vfrag<64>(vt, 32 * db, 32 + 16 * st + 4 * h, lane), pb, o[db]);
;     }
; template <int KIND  > ...
;     ...
;         if (KIND == 3) {
;             wdone = wdone || (wave_on ? (__all(Rr < -152.0f) != 0) : true);
;             if (lane == 0) dflag[(it & 1) * 8 + wv] = wdone ? 1 : 0;
;         }
;         const int np = par ^ 2;
;         if (tt - 2 >= t_lo) tile_store<64>(TA, L + np * 9216, L + 36864 + np * 9216, tid);
;         if (tt - 3 >= t_lo) tile_store<64>(TB, L + (np + 1) * 9216, L + 36864 + (np + 1) * 9216, tid);
;         if (tt - 4 >= t_lo) tile_load<64>(TA, Kp, kpitch, Vp, vpitch, (tt - 4) * 64, tid);
;         if (tt - 5 >= t_lo) tile_load<64>(TB, Kp, kpitch, Vp, vpitch, (tt - 5) * 64, tid);
;         par = np;
;     }
	v_add_f32_e32 v61, v90, v97
	s_waitcnt lgkmcnt(0)
	v_cndmask_b32_e64 v47, 0, v46, s[12:13]
	v_add_f32_e32 v47, v44, v47
	v_add_f32_e32 v49, v49, v47
	v_add_f32_e32 v47, v55, v47
	v_add_f32_e32 v48, v48, v47
	v_add_f32_e32 v47, v57, v47
	v_add_f32_e32 v50, v96, v47
	v_add_f32_e32 v47, v51, v47
	v_add_f32_e32 v37, v37, v47
	v_exp_f32_e32 v47, v37
	v_add_f32_e32 v37, v45, v46
	v_add_f32_e32 v37, v44, v37
	v_cndmask_b32_e64 v44, 0, v97, s[12:13]
	v_add_f32_e32 v44, v44, v37
	v_add_f32_e32 v45, v95, v44
	v_add_f32_e32 v44, v94, v44
	v_exp_f32_e32 v46, v45
	v_add_f32_e32 v45, v93, v44
	v_add_f32_e32 v44, v92, v44
	v_add_f32_e32 v43, v43, v44
	v_exp_f32_e32 v52, v43
	v_add_f32_e32 v43, v91, v44
	v_add_f32_e32 v42, v42, v43
	v_exp_f32_e32 v51, v45
	v_exp_f32_e32 v53, v42
	v_pk_add_f32 v[42:43], v[60:61], v[36:37]
	v_pk_add_f32 v[44:45], v[58:59], v[34:35]
	v_cndmask_b32_e64 v55, 0, v35, s[12:13]
	v_pk_add_f32 v[44:45], v[44:45], v[42:43]
	ds_bpermute_b32 v35, v86, v44
	v_add_f32_e32 v37, v55, v43
	v_add_f32_e32 v41, v41, v37
	v_add_f32_e32 v37, v89, v37
	v_add_f32_e32 v40, v40, v37
	v_add_f32_e32 v37, v88, v37
	v_add_f32_e32 v39, v39, v37
	v_add_f32_e32 v37, v87, v37
	v_add_f32_e32 v37, v38, v37
	s_waitcnt lgkmcnt(0)
	v_cndmask_b32_e64 v38, 0, v35, s[12:13]
	v_add_f32_e32 v38, v38, v45
	v_add_f32_e32 v36, v36, v38
	v_add_f32_e32 v42, v85, v38
	v_add_f32_e32 v38, v84, v36
	v_exp_f32_e32 v41, v41
	v_exp_f32_e32 v40, v40
	v_exp_f32_e32 v39, v39
	v_exp_f32_e32 v37, v37
	v_exp_f32_e32 v42, v42
	v_exp_f32_e32 v38, v38
	v_add_f32_e32 v36, v60, v36
	v_add_f32_e32 v34, v34, v36
	v_add_f32_e32 v43, v83, v36
	v_add_f32_e32 v34, v82, v34
	v_add_f32_e32 v35, v44, v35
	v_exp_f32_e32 v43, v43
	v_exp_f32_e32 v34, v34
	v_add_f32_e32 v133, v35, v45
	v_cvt_pk_bf16_f32 v35, v38, v42
	v_cvt_pk_bf16_f32 v36, v37, v39
	v_cvt_pk_bf16_f32 v37, v40, v41
	ds_read_b64_tr_b16 v[38:39], v70 offset:46080
	ds_read_b64_tr_b16 v[40:41], v70 offset:47232
	v_cvt_pk_bf16_f32 v34, v34, v43
	v_exp_f32_e32 v49, v49
	v_exp_f32_e32 v48, v48
	s_waitcnt lgkmcnt(0)
	v_mfma_f32_32x32x16_bf16 v[18:33], v[38:41], v[34:37], v[18:33]
	ds_read_b64_tr_b16 v[38:39], v70 offset:46144
	ds_read_b64_tr_b16 v[40:41], v70 offset:47296
	v_exp_f32_e32 v50, v50
	s_waitcnt lgkmcnt(0)
	v_mfma_f32_32x32x16_bf16 v[2:17], v[38:41], v[34:37], v[2:17]
	ds_read_b64_tr_b16 v[38:39], v70 offset:48384
	ds_read_b64_tr_b16 v[40:41], v70 offset:49536
	v_cvt_pk_bf16_f32 v34, v53, v52
	v_cvt_pk_bf16_f32 v35, v51, v46
	v_cvt_pk_bf16_f32 v36, v47, v50
	v_cvt_pk_bf16_f32 v37, v48, v49
	s_waitcnt lgkmcnt(0)
	s_nop 0
	v_mfma_f32_32x32x16_bf16 v[18:33], v[38:41], v[34:37], v[18:33]
	ds_read_b64_tr_b16 v[38:39], v70 offset:48448
	ds_read_b64_tr_b16 v[40:41], v70 offset:49600
	s_waitcnt lgkmcnt(0)
	v_mfma_f32_32x32x16_bf16 v[2:17], v[38:41], v[34:37], v[2:17]
	ds_read_b64_tr_b16 v[38:39], v70 offset:50688
	ds_read_b64_tr_b16 v[40:41], v70 offset:51840
	v_cvt_pk_bf16_f32 v34, v71, v73
	v_cvt_pk_bf16_f32 v35, v56, v54
	v_cvt_pk_bf16_f32 v36, v81, v80
	v_cvt_pk_bf16_f32 v37, v79, v78
	s_waitcnt lgkmcnt(0)
	s_nop 0
	v_mfma_f32_32x32x16_bf16 v[18:33], v[38:41], v[34:37], v[18:33]
	ds_read_b64_tr_b16 v[38:39], v70 offset:50752
	ds_read_b64_tr_b16 v[40:41], v70 offset:51904
	s_waitcnt lgkmcnt(0)
	v_mfma_f32_32x32x16_bf16 v[2:17], v[38:41], v[34:37], v[2:17]
	ds_read_b64_tr_b16 v[38:39], v70 offset:52992
	ds_read_b64_tr_b16 v[40:41], v70 offset:54144
	v_cvt_pk_bf16_f32 v34, v66, v69
	v_cvt_pk_bf16_f32 v35, v68, v67
	v_cvt_pk_bf16_f32 v36, v65, v64
	v_cvt_pk_bf16_f32 v37, v63, v62
	s_waitcnt lgkmcnt(0)
	s_nop 0
	v_mfma_f32_32x32x16_bf16 v[18:33], v[38:41], v[34:37], v[18:33]
	ds_read_b64_tr_b16 v[38:39], v70 offset:53056
	ds_read_b64_tr_b16 v[40:41], v70 offset:54208
	s_waitcnt lgkmcnt(0)
	v_mfma_f32_32x32x16_bf16 v[2:17], v[38:41], v[34:37], v[2:17]
	s_or_b64 exec, exec, s[18:19]
	s_andn2_b64 vcc, exec, s[58:59]
	s_mov_b64 s[18:19], -1
	s_cbranch_vccz .LBB0_626
